# sandwich-norm passes keep the residual stream as XN plus one f32 (1/r2) per row instead of XN and a second bf16 copy of h: 67 MB fewer stores in three of the four norm passes
# speedup vs baseline: 1.0095x; 1.0095x over previous
.LBB0_1697:
	s_waitcnt vmcnt(11)
	v_lshlrev_b32_e32 v142, 16, v132
	v_and_b32_e32 v143, 0xffff0000, v132
	v_lshlrev_b32_e32 v132, 16, v133
	v_and_b32_e32 v133, 0xffff0000, v133
	v_mul_f32_e32 v144, v133, v133
	v_lshlrev_b32_e32 v147, 16, v131
	v_lshlrev_b32_e32 v146, 16, v130
	v_and_b32_e32 v131, 0xffff0000, v131
	v_and_b32_e32 v130, 0xffff0000, v130
	v_lshlrev_b32_e32 v153, 16, v126
	v_mul_f32_e32 v152, v143, v143
	v_pk_fma_f32 v[144:145], v[132:133], v[132:133], v[144:145] op_sel_hi:[1,1,0]
	v_pk_mul_f32 v[148:149], v[130:131], v[130:131]
	v_pk_fma_f32 v[156:157], v[142:143], v[142:143], v[152:153] op_sel_hi:[1,1,0]
	v_pk_fma_f32 v[148:149], v[146:147], v[146:147], v[148:149]
	v_and_b32_e32 v155, 0xffff0000, v126
	v_mov_b32_e32 v152, v156
	v_mov_b32_e32 v158, v144
	v_mov_b32_e32 v159, v153
	v_mul_f32_e32 v141, v155, v155
	v_pk_add_f32 v[144:145], v[156:157], v[144:145]
	v_pk_mul_f32 v[156:157], v[152:153], v[158:159]
	v_pk_add_f32 v[148:149], v[148:149], v[148:149] op_sel:[0,1] op_sel_hi:[1,0]
	v_lshlrev_b32_e32 v150, 16, v128
	v_and_b32_e32 v151, 0xffff0000, v128
	v_lshlrev_b32_e32 v128, 16, v129
	v_and_b32_e32 v129, 0xffff0000, v129
	v_mov_b32_e32 v145, v157
	v_mov_b32_e32 v149, v141
	v_lshlrev_b32_e32 v126, 16, v127
	v_and_b32_e32 v127, 0xffff0000, v127
	v_pk_add_f32 v[144:145], v[144:145], v[148:149]
	v_mul_f32_e32 v148, v151, v151
	v_mul_f32_e32 v152, v129, v129
	v_mul_f32_e32 v154, v126, v126
	v_mul_f32_e32 v160, v127, v127
	v_pk_fma_f32 v[148:149], v[150:151], v[150:151], v[148:149] op_sel_hi:[1,1,0]
	v_pk_fma_f32 v[156:157], v[128:129], v[128:129], v[152:153] op_sel_hi:[1,1,0]
	v_mov_b32_e32 v149, v154
	v_mov_b32_e32 v157, v160
	v_pk_add_f32 v[148:149], v[148:149], v[156:157]
	s_waitcnt vmcnt(10)
	v_lshlrev_b32_e32 v159, 16, v123
	v_pk_add_f32 v[144:145], v[144:145], v[148:149]
	v_lshlrev_b32_e32 v149, 16, v125
	v_lshlrev_b32_e32 v148, 16, v124
	v_and_b32_e32 v125, 0xffff0000, v125
	v_and_b32_e32 v124, 0xffff0000, v124
	v_pk_mul_f32 v[156:157], v[124:125], v[124:125]
	v_lshlrev_b32_e32 v158, 16, v122
	v_pk_fma_f32 v[156:157], v[148:149], v[148:149], v[156:157]
	v_and_b32_e32 v123, 0xffff0000, v123
	v_pk_add_f32 v[156:157], v[156:157], v[156:157] op_sel:[0,1] op_sel_hi:[1,0]
	v_and_b32_e32 v122, 0xffff0000, v122
	s_waitcnt vmcnt(8)
	v_lshlrev_b32_e32 v173, 16, v118
	v_pk_add_f32 v[144:145], v[144:145], v[144:145] op_sel:[0,1] op_sel_hi:[1,0]
	v_pk_mul_f32 v[160:161], v[122:123], v[122:123]
	v_mov_b32_e32 v172, v144
	v_mov_b32_e32 v176, v156
	v_mov_b32_e32 v177, v173
	v_pk_fma_f32 v[160:161], v[158:159], v[158:159], v[160:161]
	v_and_b32_e32 v175, 0xffff0000, v118
	v_pk_add_f32 v[144:145], v[144:145], v[156:157]
	v_pk_mul_f32 v[156:157], v[172:173], v[176:177]
	v_and_b32_e32 v171, 0xffff0000, v120
	v_mul_f32_e32 v141, v175, v175
	v_mov_b32_e32 v145, v157
	v_pk_add_f32 v[156:157], v[160:161], v[160:161] op_sel:[0,1] op_sel_hi:[1,0]
	v_lshlrev_b32_e32 v170, 16, v120
	v_lshlrev_b32_e32 v120, 16, v121
	v_and_b32_e32 v121, 0xffff0000, v121
	v_mov_b32_e32 v157, v141
	v_mul_f32_e32 v152, v171, v171
	v_lshlrev_b32_e32 v118, 16, v119
	v_and_b32_e32 v119, 0xffff0000, v119
	v_pk_add_f32 v[144:145], v[144:145], v[156:157]
	v_pk_fma_f32 v[156:157], v[170:171], v[170:171], v[152:153] op_sel_hi:[1,1,0]
	v_mul_f32_e32 v152, v121, v121
	v_mul_f32_e32 v154, v118, v118
	v_mul_f32_e32 v163, v119, v119
	v_pk_fma_f32 v[160:161], v[120:121], v[120:121], v[152:153] op_sel_hi:[1,1,0]
	v_mov_b32_e32 v157, v154
	v_mov_b32_e32 v161, v163
	v_pk_add_f32 v[156:157], v[156:157], v[160:161]
	v_mov_b32_e32 v154, v153
	v_pk_add_f32 v[144:145], v[144:145], v[156:157]
	v_mov_b32_e32 v174, v173
	v_add_f32_e32 v141, v144, v145
	ds_bpermute_b32 v144, v134, v141
	s_waitcnt lgkmcnt(0)
	v_add_f32_e32 v141, v141, v144
	ds_bpermute_b32 v144, v135, v141
	s_waitcnt lgkmcnt(0)
	v_add_f32_e32 v141, v141, v144
	ds_bpermute_b32 v144, v136, v141
	s_waitcnt lgkmcnt(0)
	v_add_f32_e32 v141, v141, v144
	ds_bpermute_b32 v144, v137, v141
	s_waitcnt lgkmcnt(0)
	v_add_f32_e32 v141, v141, v144
	ds_bpermute_b32 v144, v138, v141
	s_waitcnt lgkmcnt(0)
	v_add_f32_e32 v141, v141, v144
	ds_bpermute_b32 v144, v139, v141
	s_waitcnt lgkmcnt(0)
	v_add_f32_e32 v141, v141, v144
	v_fmamk_f32 v141, v141, 0x3a000000, v140
	v_mul_f32_e32 v144, 0x4b800000, v141
	v_cmp_gt_f32_e32 vcc, s20, v141
	s_nop 1
	v_cndmask_b32_e32 v141, v141, v144, vcc
	v_rsq_f32_e32 v141, v141
	s_nop 0
	v_mul_f32_e32 v144, 0x45800000, v141
	v_cndmask_b32_e32 v144, v141, v144, vcc
	v_pk_mul_f32 v[132:133], v[144:145], v[132:133] op_sel_hi:[0,1]
	s_waitcnt vmcnt(0)
	v_pk_fma_f32 v[96:97], v[4:5], v[132:133], v[96:97]
	v_mov_b32_e32 v132, v146
	v_mov_b32_e32 v133, v130
	v_pk_mul_f32 v[142:143], v[144:145], v[142:143] op_sel_hi:[0,1]
	v_pk_mul_f32 v[132:133], v[144:145], v[132:133] op_sel_hi:[0,1]
	v_mov_b32_e32 v130, v147
	v_pk_fma_f32 v[94:95], v[2:3], v[142:143], v[94:95]
	v_pk_mul_f32 v[130:131], v[144:145], v[130:131] op_sel_hi:[0,1]
	v_pk_fma_f32 v[90:91], v[6:7], v[132:133], v[90:91]
	v_pk_fma_f32 v[92:93], v[8:9], v[130:131], v[92:93]
	v_mov_b32_e32 v132, v95
	v_mov_b32_e32 v133, v91
	v_mov_b32_e32 v130, v94
	v_mov_b32_e32 v131, v90
	v_pk_mul_f32 v[132:133], v[132:133], v[132:133]
	v_mov_b32_e32 v142, v97
	v_mov_b32_e32 v143, v93
	v_pk_fma_f32 v[130:131], v[130:131], v[130:131], v[132:133]
	v_mov_b32_e32 v132, v96
	v_mov_b32_e32 v133, v92
	v_pk_mul_f32 v[142:143], v[142:143], v[142:143]
	v_pk_mul_f32 v[128:129], v[144:145], v[128:129] op_sel_hi:[0,1]
	v_pk_fma_f32 v[132:133], v[132:133], v[132:133], v[142:143]
	v_pk_fma_f32 v[88:89], v[12:13], v[128:129], v[88:89]
	v_pk_add_f32 v[130:131], v[130:131], v[132:133]
	v_pk_mul_f32 v[132:133], v[144:145], v[150:151] op_sel_hi:[0,1]
	v_pk_fma_f32 v[86:87], v[10:11], v[132:133], v[86:87]
	v_pk_mul_f32 v[128:129], v[88:89], v[88:89]
	v_pk_mul_f32 v[132:133], v[86:87], v[86:87]
	v_pk_mul_f32 v[126:127], v[126:127], v[144:145] op_sel_hi:[1,0]
	v_pk_mov_b32 v[142:143], v[132:133], v[128:129] op_sel:[1,0]
	v_mov_b32_e32 v133, v129
	v_pk_add_f32 v[128:129], v[142:143], v[132:133]
	v_pk_mul_f32 v[132:133], v[154:155], v[144:145] op_sel_hi:[1,0]
	v_pk_fma_f32 v[84:85], v[16:17], v[126:127], v[84:85]
	v_pk_fma_f32 v[82:83], v[14:15], v[132:133], v[82:83]
	v_mov_b32_e32 v142, v148
	v_mul_f32_e32 v126, v82, v82
	v_pk_fma_f32 v[126:127], v[82:83], v[82:83], v[126:127] op_sel_hi:[1,1,0]
	v_mov_b32_e32 v143, v124
	v_mov_b32_e32 v124, v149
	v_mul_f32_e32 v126, v84, v84
	v_pk_mul_f32 v[142:143], v[144:145], v[142:143] op_sel_hi:[0,1]
	v_pk_mul_f32 v[124:125], v[144:145], v[124:125] op_sel_hi:[0,1]
	v_pk_add_f32 v[130:131], v[130:131], v[130:131] op_sel_hi:[0,1]
	v_pk_add_f32 v[128:129], v[128:129], v[128:129] op_sel_hi:[0,1]
	v_pk_fma_f32 v[132:133], v[84:85], v[84:85], v[126:127] op_sel_hi:[1,1,0]
	v_pk_fma_f32 v[80:81], v[20:21], v[124:125], v[80:81]
	v_pk_fma_f32 v[78:79], v[18:19], v[142:143], v[78:79]
	v_mul_f32_e32 v128, v80, v80
	v_mul_f32_e32 v126, v78, v78
	v_mul_f32_e32 v132, v79, v79
	v_mul_f32_e32 v130, v81, v81
	v_pk_add_f32 v[124:125], v[126:127], v[132:133]
	v_pk_add_f32 v[126:127], v[128:129], v[130:131]
	v_pk_mul_f32 v[120:121], v[144:145], v[120:121] op_sel_hi:[0,1]
	v_pk_add_f32 v[124:125], v[124:125], v[126:127]
	v_mov_b32_e32 v126, v159
	v_mov_b32_e32 v127, v123
	v_mov_b32_e32 v159, v122
	v_pk_mul_f32 v[126:127], v[144:145], v[126:127] op_sel_hi:[0,1]
	v_pk_mul_f32 v[122:123], v[144:145], v[158:159] op_sel_hi:[0,1]
	v_pk_fma_f32 v[74:75], v[22:23], v[122:123], v[74:75]
	v_pk_fma_f32 v[76:77], v[24:25], v[126:127], v[76:77]
	v_pk_mul_f32 v[126:127], v[74:75], v[74:75]
	v_pk_mul_f32 v[122:123], v[76:77], v[76:77]
	v_pk_fma_f32 v[72:73], v[28:29], v[120:121], v[72:73]
	v_pk_mov_b32 v[128:129], v[126:127], v[122:123] op_sel:[1,0]
	v_mov_b32_e32 v127, v123
	v_pk_add_f32 v[122:123], v[128:129], v[126:127]
	v_pk_mul_f32 v[126:127], v[144:145], v[170:171] op_sel_hi:[0,1]
	v_pk_fma_f32 v[70:71], v[26:27], v[126:127], v[70:71]
	v_pk_mul_f32 v[128:129], v[174:175], v[144:145] op_sel_hi:[1,0]
	v_mul_f32_e32 v120, v70, v70
	v_pk_fma_f32 v[120:121], v[70:71], v[70:71], v[120:121] op_sel_hi:[1,1,0]
	v_pk_mul_f32 v[118:119], v[118:119], v[144:145] op_sel_hi:[1,0]
	v_mul_f32_e32 v120, v72, v72
	v_pk_add_f32 v[124:125], v[124:125], v[124:125] op_sel_hi:[0,1]
	v_pk_add_f32 v[122:123], v[122:123], v[122:123] op_sel_hi:[0,1]
	v_pk_fma_f32 v[126:127], v[72:73], v[72:73], v[120:121] op_sel_hi:[1,1,0]
	v_pk_fma_f32 v[68:69], v[32:33], v[118:119], v[68:69]
	v_pk_fma_f32 v[66:67], v[30:31], v[128:129], v[66:67]
	v_mul_f32_e32 v122, v68, v68
	v_mul_f32_e32 v120, v66, v66
	v_mul_f32_e32 v126, v67, v67
	v_mul_f32_e32 v124, v69, v69
	v_pk_add_f32 v[118:119], v[120:121], v[126:127]
	v_pk_add_f32 v[120:121], v[122:123], v[124:125]
	v_cvt_pk_bf16_f32 v122, v94, v95
	v_pk_add_f32 v[118:119], v[118:119], v[120:121]
	v_lshl_add_u64 v[120:121], s[6:7], 0, v[98:99]
	v_add_f32_e32 v118, v118, v119
	ds_bpermute_b32 v119, v134, v118
	v_cvt_pk_bf16_f32 v123, v96, v97
	s_add_u32 s6, s6, s12
	s_addc_u32 s7, s7, s13
	s_add_u32 s1, s1, s8
	s_waitcnt lgkmcnt(0)
	v_add_f32_e32 v118, v118, v119
	ds_bpermute_b32 v119, v135, v118
	s_addc_u32 s3, s3, s9
	s_add_u32 s16, s16, s12
	s_addc_u32 s17, s17, s13
	v_mov_b64_e32 v[132:133], v[116:117]
	s_waitcnt lgkmcnt(0)
	v_add_f32_e32 v118, v118, v119
	ds_bpermute_b32 v119, v136, v118
	v_mov_b64_e32 v[130:131], v[114:115]
	v_mov_b64_e32 v[128:129], v[112:113]
	v_mov_b64_e32 v[126:127], v[110:111]
	s_waitcnt lgkmcnt(0)
	v_add_f32_e32 v118, v118, v119
	ds_bpermute_b32 v119, v137, v118
	s_waitcnt lgkmcnt(0)
	v_add_f32_e32 v118, v118, v119
	ds_bpermute_b32 v119, v138, v118
	s_waitcnt lgkmcnt(0)
	v_add_f32_e32 v118, v118, v119
	ds_bpermute_b32 v119, v139, v118
	s_waitcnt lgkmcnt(0)
	v_add_f32_e32 v118, v118, v119
	v_fmamk_f32 v118, v118, 0x3a000000, v140
	v_mul_f32_e32 v119, 0x4b800000, v118
	v_cmp_gt_f32_e32 vcc, s20, v118
	s_nop 1
	v_cndmask_b32_e32 v118, v118, v119, vcc
	v_rsq_f32_e32 v118, v118
	s_nop 0
	v_mul_f32_e32 v119, 0x45800000, v118
	v_cndmask_b32_e32 v118, v118, v119, vcc
	v_rcp_f32_e32 v179, v118
	v_add_co_u32_e32 v124, vcc, 0x2f883000, v120
	v_pk_mul_f32 v[94:95], v[94:95], v[118:119] op_sel_hi:[1,0]
	s_nop 0
	v_addc_co_u32_e32 v125, vcc, 0, v121, vcc
	v_pk_mul_f32 v[96:97], v[96:97], v[118:119] op_sel_hi:[1,0]
	v_cvt_pk_bf16_f32 v94, v94, v95
	v_cvt_pk_bf16_f32 v95, v96, v97
	v_add_co_u32_e32 v96, vcc, s22, v120
	s_nop 0
	v_addc_co_u32_e32 v97, vcc, 0, v121, vcc
	global_store_dwordx2 v[96:97], v[94:95], off
	v_cvt_pk_bf16_f32 v94, v90, v91
	v_cvt_pk_bf16_f32 v95, v92, v93
	v_pk_mul_f32 v[90:91], v[90:91], v[118:119] op_sel_hi:[1,0]
	v_pk_mul_f32 v[92:93], v[92:93], v[118:119] op_sel_hi:[1,0]
	v_cvt_pk_bf16_f32 v90, v90, v91
	v_cvt_pk_bf16_f32 v91, v92, v93
	global_store_dwordx2 v[96:97], v[90:91], off offset:512
	v_cvt_pk_bf16_f32 v90, v86, v87
	v_cvt_pk_bf16_f32 v91, v88, v89
	v_pk_mul_f32 v[86:87], v[86:87], v[118:119] op_sel_hi:[1,0]
	v_pk_mul_f32 v[88:89], v[88:89], v[118:119] op_sel_hi:[1,0]
	v_cvt_pk_bf16_f32 v86, v86, v87
	v_cvt_pk_bf16_f32 v87, v88, v89
	global_store_dwordx2 v[96:97], v[86:87], off offset:1024
	v_cvt_pk_bf16_f32 v86, v82, v83
	v_cvt_pk_bf16_f32 v87, v84, v85
	v_pk_mul_f32 v[82:83], v[82:83], v[118:119] op_sel_hi:[1,0]
	v_pk_mul_f32 v[84:85], v[84:85], v[118:119] op_sel_hi:[1,0]
	v_cvt_pk_bf16_f32 v82, v82, v83
	v_cvt_pk_bf16_f32 v83, v84, v85
	global_store_dwordx2 v[96:97], v[82:83], off offset:1536
	v_cvt_pk_bf16_f32 v82, v78, v79
	v_cvt_pk_bf16_f32 v83, v80, v81
	v_pk_mul_f32 v[78:79], v[78:79], v[118:119] op_sel_hi:[1,0]
	v_pk_mul_f32 v[80:81], v[80:81], v[118:119] op_sel_hi:[1,0]
	v_cvt_pk_bf16_f32 v78, v78, v79
	v_cvt_pk_bf16_f32 v79, v80, v81
	global_store_dwordx2 v[96:97], v[78:79], off offset:2048
	v_cvt_pk_bf16_f32 v78, v74, v75
	v_cvt_pk_bf16_f32 v79, v76, v77
	v_pk_mul_f32 v[74:75], v[74:75], v[118:119] op_sel_hi:[1,0]
	v_pk_mul_f32 v[76:77], v[76:77], v[118:119] op_sel_hi:[1,0]
	v_cvt_pk_bf16_f32 v74, v74, v75
	v_cvt_pk_bf16_f32 v75, v76, v77
	global_store_dwordx2 v[96:97], v[74:75], off offset:2560
	v_cvt_pk_bf16_f32 v74, v70, v71
	v_cvt_pk_bf16_f32 v75, v72, v73
	v_pk_mul_f32 v[70:71], v[70:71], v[118:119] op_sel_hi:[1,0]
	v_pk_mul_f32 v[72:73], v[72:73], v[118:119] op_sel_hi:[1,0]
	v_cvt_pk_bf16_f32 v70, v70, v71
	v_cvt_pk_bf16_f32 v71, v72, v73
	global_store_dwordx2 v[96:97], v[70:71], off offset:3072
	v_cvt_pk_bf16_f32 v70, v66, v67
	v_cvt_pk_bf16_f32 v71, v68, v69
	v_pk_mul_f32 v[66:67], v[66:67], v[118:119] op_sel_hi:[1,0]
	v_pk_mul_f32 v[68:69], v[68:69], v[118:119] op_sel_hi:[1,0]
	v_cvt_pk_bf16_f32 v66, v66, v67
	v_cvt_pk_bf16_f32 v67, v68, v69
	global_store_dwordx2 v[96:97], v[66:67], off offset:3584
	global_store_dword v[124:125], v179, off offset:0
	v_mov_b64_e32 v[68:69], v[52:53]
	v_mov_b64_e32 v[72:73], v[56:57]
	v_mov_b64_e32 v[76:77], v[60:61]
	v_mov_b64_e32 v[80:81], v[64:65]
	v_mov_b64_e32 v[84:85], v[36:37]
	v_mov_b64_e32 v[88:89], v[40:41]
	v_mov_b64_e32 v[92:93], v[44:45]
	v_mov_b64_e32 v[96:97], v[48:49]
	s_andn2_b64 vcc, exec, s[18:19]
	v_mov_b64_e32 v[66:67], v[50:51]
	v_mov_b64_e32 v[70:71], v[54:55]
	v_mov_b64_e32 v[74:75], v[58:59]
	v_mov_b64_e32 v[78:79], v[62:63]
	v_mov_b64_e32 v[82:83], v[34:35]
	v_mov_b64_e32 v[86:87], v[38:39]
	v_mov_b64_e32 v[90:91], v[42:43]
	v_mov_b64_e32 v[94:95], v[46:47]
	v_mov_b64_e32 v[124:125], v[108:109]
	v_mov_b64_e32 v[122:123], v[106:107]
	v_mov_b64_e32 v[120:121], v[104:105]
	v_mov_b64_e32 v[118:119], v[102:103]
	s_cbranch_vccz .LBB0_1700

.LBB0_2004:
	s_or_b64 exec, exec, s[0:1]
	s_mov_b64 s[4:5], s[92:93]
	s_waitcnt lgkmcnt(0)
	v_mov_b32_e32 v2, v0
	v_readlane_b32 s0, v254, 9
	s_barrier
	v_readlane_b32 s1, v254, 10
	s_add_i32 s0, s0, s1
	s_cmpk_gt_i32 s0, 0x407f
	s_cbranch_scc1 .LBB0_2009
	s_load_dwordx2 s[6:7], s[4:5], 0x48
	s_load_dwordx2 s[8:9], s[4:5], 0xd0
	v_and_b32_e32 v34, 63, v2
	v_lshlrev_b32_e32 v26, 4, v34
	v_or_b32_e32 v10, 0x400, v26
	s_waitcnt lgkmcnt(0)
	s_add_u32 s4, s6, 0x6000
	s_addc_u32 s5, s7, 0
	v_or_b32_e32 v18, 0x800, v26
	v_or_b32_e32 v19, 0xc00, v26
	v_or_b32_e32 v27, 0x1000, v26
	v_or_b32_e32 v28, 0x1400, v26
	v_or_b32_e32 v35, 0x1800, v26
	s_ashr_i32 s1, s0, 31
	global_load_dwordx4 v[2:5], v26, s[4:5]
	global_load_dwordx4 v[6:9], v10, s[4:5]
	s_nop 0
	global_load_dwordx4 v[10:13], v18, s[4:5]
	global_load_dwordx4 v[14:17], v19, s[4:5]
	s_nop 0
	global_load_dwordx4 v[18:21], v27, s[4:5]
	global_load_dwordx4 v[22:25], v28, s[4:5]
	v_or_b32_e32 v36, 0x1c00, v26
	global_load_dwordx4 v[26:29], v35, s[4:5]
	global_load_dwordx4 v[30:33], v36, s[4:5]
	s_lshl_b64 s[4:5], s[0:1], 12
	s_add_u32 s4, s8, s4
	v_lshlrev_b32_e32 v34, 3, v34
	v_mov_b32_e32 v35, 0
	s_addc_u32 s5, s9, s5
	v_lshl_add_u64 v[36:37], s[4:5], 0, v[34:35]
	v_add_co_u32_e32 v178, vcc, 0x2f883000, v36
	s_nop 1
	v_addc_co_u32_e32 v179, vcc, 0, v37, vcc
	global_load_dword v180, v[178:179], off offset:0
	s_mov_b32 s1, 0x2b783000
	s_mov_b64 s[6:7], 0x2b783000
	v_add_co_u32_e32 v40, vcc, s1, v36
	v_lshl_add_u64 v[38:39], v[36:37], 0, s[6:7]
	s_nop 0
	v_addc_co_u32_e32 v41, vcc, 0, v37, vcc
	s_mov_b64 s[6:7], 0xc803000
	s_mov_b32 s1, 0xc803000
	global_load_dwordx2 v[94:95], v[38:39], off offset:512
	global_load_dwordx2 v[92:93], v[38:39], off offset:1024
	global_load_dwordx2 v[90:91], v[38:39], off offset:1536
	global_load_dwordx2 v[88:89], v[38:39], off offset:2048
	global_load_dwordx2 v[96:97], v[40:41], off
	global_load_dwordx2 v[86:87], v[38:39], off offset:2560
	global_load_dwordx2 v[84:85], v[38:39], off offset:3072
	global_load_dwordx2 v[82:83], v[38:39], off offset:3584
	v_lshl_add_u64 v[38:39], v[36:37], 0, s[6:7]
	v_add_co_u32_e32 v36, vcc, s1, v36
	s_add_i32 s10, s0, s94
	s_nop 0
	v_addc_co_u32_e32 v37, vcc, 0, v37, vcc
	global_load_dwordx2 v[80:81], v[38:39], off offset:512
	global_load_dwordx2 v[78:79], v[38:39], off offset:1024
	global_load_dwordx2 v[76:77], v[38:39], off offset:1536
	global_load_dwordx2 v[74:75], v[38:39], off offset:2048
	global_load_dwordx2 v[98:99], v[36:37], off
	global_load_dwordx2 v[72:73], v[38:39], off offset:2560
	global_load_dwordx2 v[70:71], v[38:39], off offset:3072
	global_load_dwordx2 v[68:69], v[38:39], off offset:3584
	v_mbcnt_lo_u32_b32 v36, -1, 0
	v_mbcnt_hi_u32_b32 v36, -1, v36
	v_and_b32_e32 v37, 64, v36
	v_add_u32_e32 v37, 64, v37
	v_xor_b32_e32 v38, 1, v36
	v_cmp_lt_i32_e32 vcc, v38, v37
	s_ashr_i32 s95, s94, 31
	s_ashr_i32 s11, s10, 31
	v_cndmask_b32_e32 v38, v36, v38, vcc
	v_lshlrev_b32_e32 v100, 2, v38
	v_xor_b32_e32 v38, 2, v36
	v_cmp_lt_i32_e32 vcc, v38, v37
	s_lshl_b64 s[6:7], s[94:95], 12
	s_lshl_b64 s[10:11], s[10:11], 12
	v_cndmask_b32_e32 v38, v36, v38, vcc
	v_lshlrev_b32_e32 v101, 2, v38
	v_xor_b32_e32 v38, 4, v36
	v_cmp_lt_i32_e32 vcc, v38, v37
	s_add_u32 s8, s8, s10
	s_addc_u32 s9, s9, s11
	v_cndmask_b32_e32 v38, v36, v38, vcc
	v_lshlrev_b32_e32 v102, 2, v38
	v_xor_b32_e32 v38, 8, v36
	v_cmp_lt_i32_e32 vcc, v38, v37
	v_mov_b32_e32 v106, 0x358637bd
	s_mov_b32 s3, 0x800000
	v_cndmask_b32_e32 v38, v36, v38, vcc
	v_lshlrev_b32_e32 v103, 2, v38
	v_xor_b32_e32 v38, 16, v36
	v_cmp_lt_i32_e32 vcc, v38, v37
	s_mov_b32 s12, 0xc803000
	s_nop 0
	v_cndmask_b32_e32 v38, v36, v38, vcc
	v_lshlrev_b32_e32 v104, 2, v38
	v_xor_b32_e32 v38, 32, v36
	v_cmp_lt_i32_e32 vcc, v38, v37
	s_nop 1
	v_cndmask_b32_e32 v36, v36, v38, vcc
	v_lshlrev_b32_e32 v105, 2, v36
	s_branch .LBB0_2007
.LBB0_2006:
	s_waitcnt vmcnt(11)
	v_lshlrev_b32_e32 v110, 16, v96
	v_and_b32_e32 v111, 0xffff0000, v96
	v_lshlrev_b32_e32 v96, 16, v97
	v_and_b32_e32 v97, 0xffff0000, v97
	v_mul_f32_e32 v112, v97, v97
	v_lshlrev_b32_e32 v117, 16, v95
	v_lshlrev_b32_e32 v116, 16, v94
	v_and_b32_e32 v95, 0xffff0000, v95
	v_and_b32_e32 v94, 0xffff0000, v94
	v_lshlrev_b32_e32 v123, 16, v90
	v_mul_f32_e32 v122, v111, v111
	v_pk_fma_f32 v[112:113], v[96:97], v[96:97], v[112:113] op_sel_hi:[1,1,0]
	v_pk_mul_f32 v[118:119], v[94:95], v[94:95]
	v_pk_fma_f32 v[126:127], v[110:111], v[110:111], v[122:123] op_sel_hi:[1,1,0]
	v_pk_fma_f32 v[118:119], v[116:117], v[116:117], v[118:119]
	v_and_b32_e32 v125, 0xffff0000, v90
	v_mov_b32_e32 v122, v126
	v_mov_b32_e32 v128, v112
	v_mov_b32_e32 v129, v123
	v_mul_f32_e32 v107, v125, v125
	v_pk_add_f32 v[112:113], v[126:127], v[112:113]
	v_pk_mul_f32 v[126:127], v[122:123], v[128:129]
	v_pk_add_f32 v[118:119], v[118:119], v[118:119] op_sel:[0,1] op_sel_hi:[1,0]
	v_lshlrev_b32_e32 v120, 16, v92
	v_and_b32_e32 v121, 0xffff0000, v92
	v_lshlrev_b32_e32 v92, 16, v93
	v_and_b32_e32 v93, 0xffff0000, v93
	v_mov_b32_e32 v113, v127
	v_mov_b32_e32 v119, v107
	v_lshlrev_b32_e32 v90, 16, v91
	v_and_b32_e32 v91, 0xffff0000, v91
	v_pk_add_f32 v[112:113], v[112:113], v[118:119]
	v_mul_f32_e32 v118, v121, v121
	v_mul_f32_e32 v122, v93, v93
	v_mul_f32_e32 v115, v90, v90
	v_mul_f32_e32 v124, v91, v91
	v_pk_fma_f32 v[118:119], v[120:121], v[120:121], v[118:119] op_sel_hi:[1,1,0]
	v_pk_fma_f32 v[126:127], v[92:93], v[92:93], v[122:123] op_sel_hi:[1,1,0]
	v_mov_b32_e32 v119, v115
	v_mov_b32_e32 v127, v124
	v_pk_add_f32 v[118:119], v[118:119], v[126:127]
	s_waitcnt vmcnt(10)
	v_lshlrev_b32_e32 v129, 16, v87
	v_pk_add_f32 v[112:113], v[112:113], v[118:119]
	v_lshlrev_b32_e32 v119, 16, v89
	v_lshlrev_b32_e32 v118, 16, v88
	v_and_b32_e32 v89, 0xffff0000, v89
	v_and_b32_e32 v88, 0xffff0000, v88
	v_pk_mul_f32 v[126:127], v[88:89], v[88:89]
	v_lshlrev_b32_e32 v128, 16, v86
	v_pk_fma_f32 v[126:127], v[118:119], v[118:119], v[126:127]
	v_and_b32_e32 v87, 0xffff0000, v87
	v_pk_add_f32 v[126:127], v[126:127], v[126:127] op_sel:[0,1] op_sel_hi:[1,0]
	v_and_b32_e32 v86, 0xffff0000, v86
	s_waitcnt vmcnt(8)
	v_lshlrev_b32_e32 v135, 16, v82
	v_pk_add_f32 v[112:113], v[112:113], v[112:113] op_sel:[0,1] op_sel_hi:[1,0]
	v_pk_mul_f32 v[130:131], v[86:87], v[86:87]
	v_mov_b32_e32 v134, v112
	v_mov_b32_e32 v138, v126
	v_mov_b32_e32 v139, v135
	v_pk_fma_f32 v[130:131], v[128:129], v[128:129], v[130:131]
	v_and_b32_e32 v137, 0xffff0000, v82
	v_pk_add_f32 v[112:113], v[112:113], v[126:127]
	v_pk_mul_f32 v[126:127], v[134:135], v[138:139]
	v_and_b32_e32 v133, 0xffff0000, v84
	v_mul_f32_e32 v107, v137, v137
	v_mov_b32_e32 v113, v127
	v_pk_add_f32 v[126:127], v[130:131], v[130:131] op_sel:[0,1] op_sel_hi:[1,0]
	v_lshlrev_b32_e32 v132, 16, v84
	v_lshlrev_b32_e32 v84, 16, v85
	v_and_b32_e32 v85, 0xffff0000, v85
	v_mov_b32_e32 v127, v107
	v_mul_f32_e32 v122, v133, v133
	v_lshlrev_b32_e32 v82, 16, v83
	v_and_b32_e32 v83, 0xffff0000, v83
	v_pk_add_f32 v[112:113], v[112:113], v[126:127]
	v_pk_fma_f32 v[126:127], v[132:133], v[132:133], v[122:123] op_sel_hi:[1,1,0]
	v_mul_f32_e32 v122, v85, v85
	v_mul_f32_e32 v115, v82, v82
	v_mul_f32_e32 v124, v83, v83
	v_pk_fma_f32 v[130:131], v[84:85], v[84:85], v[122:123] op_sel_hi:[1,1,0]
	v_mov_b32_e32 v127, v115
	v_mov_b32_e32 v131, v124
	v_pk_add_f32 v[126:127], v[126:127], v[130:131]
	s_waitcnt vmcnt(3)
	v_lshlrev_b32_e32 v108, 16, v98
	v_mul_f32_e32 v108, v180, v108
	v_pk_add_f32 v[112:113], v[112:113], v[126:127]
	v_and_b32_e32 v109, 0xffff0000, v98
	v_mul_f32_e32 v109, v180, v109
	v_add_f32_e32 v107, v112, v113
	ds_bpermute_b32 v113, v100, v107
	v_lshlrev_b32_e32 v98, 16, v99
	v_mul_f32_e32 v98, v180, v98
	v_and_b32_e32 v99, 0xffff0000, v99
	v_mul_f32_e32 v99, v180, v99
	v_lshlrev_b32_e32 v114, 16, v80
	v_mul_f32_e32 v114, v180, v114
	v_and_b32_e32 v115, 0xffff0000, v80
	v_mul_f32_e32 v115, v180, v115
	s_waitcnt lgkmcnt(0)
	v_add_f32_e32 v107, v107, v113
	ds_bpermute_b32 v122, v101, v107
	v_lshlrev_b32_e32 v80, 16, v81
	v_mul_f32_e32 v80, v180, v80
	v_and_b32_e32 v81, 0xffff0000, v81
	v_mul_f32_e32 v81, v180, v81
	v_lshlrev_b32_e32 v112, 16, v78
	v_mul_f32_e32 v112, v180, v112
	v_and_b32_e32 v113, 0xffff0000, v78
	v_mul_f32_e32 v113, v180, v113
	s_waitcnt lgkmcnt(0)
	v_add_f32_e32 v107, v107, v122
	ds_bpermute_b32 v122, v102, v107
	v_lshlrev_b32_e32 v78, 16, v79
	v_mul_f32_e32 v78, v180, v78
	v_and_b32_e32 v79, 0xffff0000, v79
	v_mul_f32_e32 v79, v180, v79
	v_mov_b32_e32 v124, v123
	v_lshlrev_b32_e32 v126, 16, v76
	v_mul_f32_e32 v126, v180, v126
	s_waitcnt lgkmcnt(0)
	v_add_f32_e32 v107, v107, v122
	ds_bpermute_b32 v122, v103, v107
	v_and_b32_e32 v127, 0xffff0000, v76
	v_mul_f32_e32 v127, v180, v127
	v_lshlrev_b32_e32 v76, 16, v77
	v_mul_f32_e32 v76, v180, v76
	v_and_b32_e32 v77, 0xffff0000, v77
	v_mul_f32_e32 v77, v180, v77
	v_lshlrev_b32_e32 v130, 16, v74
	v_mul_f32_e32 v130, v180, v130
	s_waitcnt lgkmcnt(0)
	v_add_f32_e32 v107, v107, v122
	ds_bpermute_b32 v122, v104, v107
	v_and_b32_e32 v131, 0xffff0000, v74
	v_mul_f32_e32 v131, v180, v131
	v_lshlrev_b32_e32 v74, 16, v75
	v_mul_f32_e32 v74, v180, v74
	v_and_b32_e32 v75, 0xffff0000, v75
	v_mul_f32_e32 v75, v180, v75
	s_waitcnt vmcnt(2)
	v_lshlrev_b32_e32 v138, 16, v72
	v_mul_f32_e32 v138, v180, v138
	s_waitcnt lgkmcnt(0)
	v_add_f32_e32 v107, v107, v122
	ds_bpermute_b32 v122, v105, v107
	v_and_b32_e32 v139, 0xffff0000, v72
	v_mul_f32_e32 v139, v180, v139
	v_lshlrev_b32_e32 v72, 16, v73
	v_mul_f32_e32 v72, v180, v72
	v_and_b32_e32 v73, 0xffff0000, v73
	v_mul_f32_e32 v73, v180, v73
	s_waitcnt vmcnt(1)
	v_lshlrev_b32_e32 v140, 16, v70
	v_mul_f32_e32 v140, v180, v140
	s_waitcnt lgkmcnt(0)
	v_add_f32_e32 v107, v107, v122
	v_fmamk_f32 v107, v107, 0x3a000000, v106
	v_mul_f32_e32 v122, 0x4b800000, v107
	v_cmp_gt_f32_e32 vcc, s3, v107
	v_and_b32_e32 v141, 0xffff0000, v70
	v_mul_f32_e32 v141, v180, v141
	v_lshlrev_b32_e32 v70, 16, v71
	v_mul_f32_e32 v70, v180, v70
	v_cndmask_b32_e32 v107, v107, v122, vcc
	v_rsq_f32_e32 v107, v107
	v_and_b32_e32 v71, 0xffff0000, v71
	v_mul_f32_e32 v71, v180, v71
	v_mov_b32_e32 v136, v135
	s_waitcnt vmcnt(0)
	v_lshlrev_b32_e32 v142, 16, v68
	v_mul_f32_e32 v142, v180, v142
	v_mul_f32_e32 v122, 0x45800000, v107
	v_cndmask_b32_e32 v122, v107, v122, vcc
	v_pk_mul_f32 v[110:111], v[122:123], v[110:111] op_sel_hi:[0,1]
	v_pk_mul_f32 v[96:97], v[122:123], v[96:97] op_sel_hi:[0,1]
	v_pk_fma_f32 v[96:97], v[4:5], v[96:97], v[98:99]
	v_pk_fma_f32 v[98:99], v[2:3], v[110:111], v[108:109]
	v_mov_b32_e32 v108, v116
	v_mov_b32_e32 v109, v94
	v_mov_b32_e32 v94, v117
	v_pk_mul_f32 v[108:109], v[122:123], v[108:109] op_sel_hi:[0,1]
	v_pk_mul_f32 v[94:95], v[122:123], v[94:95] op_sel_hi:[0,1]
	v_pk_fma_f32 v[80:81], v[8:9], v[94:95], v[80:81]
	v_pk_fma_f32 v[94:95], v[6:7], v[108:109], v[114:115]
	v_mov_b32_e32 v110, v99
	v_mov_b32_e32 v111, v95
	v_mov_b32_e32 v108, v98
	v_mov_b32_e32 v109, v94
	v_pk_mul_f32 v[110:111], v[110:111], v[110:111]
	v_mov_b32_e32 v114, v97
	v_mov_b32_e32 v115, v81
	v_pk_fma_f32 v[108:109], v[108:109], v[108:109], v[110:111]
	v_mov_b32_e32 v110, v96
	v_mov_b32_e32 v111, v80
	v_pk_mul_f32 v[114:115], v[114:115], v[114:115]
	v_pk_mul_f32 v[92:93], v[122:123], v[92:93] op_sel_hi:[0,1]
	v_pk_fma_f32 v[110:111], v[110:111], v[110:111], v[114:115]
	v_pk_fma_f32 v[78:79], v[12:13], v[92:93], v[78:79]
	v_pk_add_f32 v[108:109], v[108:109], v[110:111]
	v_pk_mul_f32 v[110:111], v[122:123], v[120:121] op_sel_hi:[0,1]
	v_pk_fma_f32 v[110:111], v[10:11], v[110:111], v[112:113]
	v_pk_mul_f32 v[92:93], v[78:79], v[78:79]
	v_pk_mul_f32 v[112:113], v[110:111], v[110:111]
	v_pk_mul_f32 v[90:91], v[90:91], v[122:123] op_sel_hi:[1,0]
	v_pk_mov_b32 v[114:115], v[112:113], v[92:93] op_sel:[1,0]
	v_mov_b32_e32 v113, v93
	v_pk_add_f32 v[92:93], v[114:115], v[112:113]
	v_pk_mul_f32 v[112:113], v[124:125], v[122:123] op_sel_hi:[1,0]
	v_pk_add_f32 v[92:93], v[92:93], v[92:93] op_sel_hi:[0,1]
	v_pk_fma_f32 v[76:77], v[16:17], v[90:91], v[76:77]
	v_pk_fma_f32 v[90:91], v[14:15], v[112:113], v[126:127]
	v_mov_b32_e32 v117, v88
	v_mov_b32_e32 v88, v119
	v_mul_f32_e32 v92, v90, v90
	v_pk_mul_f32 v[88:89], v[122:123], v[88:89] op_sel_hi:[0,1]
	v_pk_add_f32 v[108:109], v[108:109], v[108:109] op_sel_hi:[0,1]
	v_pk_fma_f32 v[112:113], v[90:91], v[90:91], v[92:93] op_sel_hi:[1,1,0]
	v_mul_f32_e32 v92, v76, v76
	v_mov_b32_e32 v116, v118
	v_pk_fma_f32 v[74:75], v[20:21], v[88:89], v[74:75]
	v_pk_fma_f32 v[114:115], v[76:77], v[76:77], v[92:93] op_sel_hi:[1,1,0]
	v_pk_mul_f32 v[116:117], v[122:123], v[116:117] op_sel_hi:[0,1]
	v_mul_f32_e32 v92, v74, v74
	v_mul_f32_e32 v108, v75, v75
	v_pk_fma_f32 v[88:89], v[18:19], v[116:117], v[130:131]
	v_pk_add_f32 v[92:93], v[92:93], v[108:109]
	v_mov_b32_e32 v108, v129
	v_mov_b32_e32 v109, v87
	v_mov_b32_e32 v129, v86
	v_mul_f32_e32 v112, v88, v88
	v_mul_f32_e32 v114, v89, v89
	v_pk_mul_f32 v[108:109], v[122:123], v[108:109] op_sel_hi:[0,1]
	v_pk_mul_f32 v[86:87], v[122:123], v[128:129] op_sel_hi:[0,1]
	v_pk_add_f32 v[112:113], v[112:113], v[114:115]
	v_pk_fma_f32 v[86:87], v[22:23], v[86:87], v[138:139]
	v_pk_fma_f32 v[72:73], v[24:25], v[108:109], v[72:73]
	v_pk_add_f32 v[92:93], v[112:113], v[92:93]
	v_pk_mul_f32 v[108:109], v[72:73], v[72:73]
	v_pk_mul_f32 v[112:113], v[86:87], v[86:87]
	v_pk_mul_f32 v[84:85], v[122:123], v[84:85] op_sel_hi:[0,1]
	v_pk_mov_b32 v[114:115], v[112:113], v[108:109] op_sel:[1,0]
	v_mov_b32_e32 v113, v109
	v_pk_add_f32 v[108:109], v[114:115], v[112:113]
	v_pk_mul_f32 v[112:113], v[122:123], v[132:133] op_sel_hi:[0,1]
	v_pk_add_f32 v[92:93], v[92:93], v[92:93] op_sel_hi:[0,1]
	v_pk_fma_f32 v[70:71], v[28:29], v[84:85], v[70:71]
	v_pk_fma_f32 v[84:85], v[26:27], v[112:113], v[140:141]
	v_and_b32_e32 v143, 0xffff0000, v68
	v_mul_f32_e32 v143, v180, v143
	v_mul_f32_e32 v92, v84, v84
	v_lshlrev_b32_e32 v68, 16, v69
	v_mul_f32_e32 v68, v180, v68
	v_and_b32_e32 v69, 0xffff0000, v69
	v_mul_f32_e32 v69, v180, v69
	v_pk_fma_f32 v[112:113], v[84:85], v[84:85], v[92:93] op_sel_hi:[1,1,0]
	v_mul_f32_e32 v92, v70, v70
	v_pk_mul_f32 v[116:117], v[136:137], v[122:123] op_sel_hi:[1,0]
	v_pk_mul_f32 v[82:83], v[82:83], v[122:123] op_sel_hi:[1,0]
	v_pk_add_f32 v[108:109], v[108:109], v[108:109] op_sel_hi:[0,1]
	v_pk_fma_f32 v[114:115], v[70:71], v[70:71], v[92:93] op_sel_hi:[1,1,0]
	v_pk_fma_f32 v[68:69], v[32:33], v[82:83], v[68:69]
	v_pk_fma_f32 v[82:83], v[30:31], v[116:117], v[142:143]
	v_mul_f32_e32 v108, v68, v68
	v_mul_f32_e32 v112, v82, v82
	v_mul_f32_e32 v114, v83, v83
	v_mul_f32_e32 v92, v69, v69
	v_pk_add_f32 v[112:113], v[112:113], v[114:115]
	v_pk_add_f32 v[92:93], v[108:109], v[92:93]
	v_lshl_add_u64 v[108:109], s[4:5], 0, v[34:35]
	v_pk_add_f32 v[92:93], v[112:113], v[92:93]
	v_cvt_pk_bf16_f32 v112, v98, v99
	v_add_f32_e32 v92, v92, v93
	ds_bpermute_b32 v93, v100, v92
	v_cvt_pk_bf16_f32 v113, v96, v97
	s_add_u32 s4, s4, s6
	s_addc_u32 s5, s5, s7
	s_add_u32 s8, s8, s6
	s_waitcnt lgkmcnt(0)
	v_add_f32_e32 v92, v92, v93
	ds_bpermute_b32 v93, v101, v92
	s_addc_u32 s9, s9, s7
	s_waitcnt lgkmcnt(0)
	v_add_f32_e32 v92, v92, v93
	ds_bpermute_b32 v93, v102, v92
	s_waitcnt lgkmcnt(0)
	v_add_f32_e32 v92, v92, v93
	ds_bpermute_b32 v93, v103, v92
	s_waitcnt lgkmcnt(0)
	v_add_f32_e32 v92, v92, v93
	ds_bpermute_b32 v93, v104, v92
	s_waitcnt lgkmcnt(0)
	v_add_f32_e32 v92, v92, v93
	ds_bpermute_b32 v93, v105, v92
	s_waitcnt lgkmcnt(0)
	v_add_f32_e32 v92, v92, v93
	v_fmamk_f32 v92, v92, 0x3a000000, v106
	v_mul_f32_e32 v93, 0x4b800000, v92
	v_cmp_gt_f32_e32 vcc, s3, v92
	s_nop 1
	v_cndmask_b32_e32 v92, v92, v93, vcc
	v_rsq_f32_e32 v92, v92
	s_nop 0
	v_mul_f32_e32 v93, 0x45800000, v92
	v_cndmask_b32_e32 v92, v92, v93, vcc
	v_rcp_f32_e32 v179, v92
	v_add_co_u32_e32 v114, vcc, 0x2f883000, v108
	v_pk_mul_f32 v[98:99], v[98:99], v[92:93] op_sel_hi:[1,0]
	s_nop 0
	v_addc_co_u32_e32 v115, vcc, 0, v109, vcc
	v_pk_mul_f32 v[96:97], v[96:97], v[92:93] op_sel_hi:[1,0]
	v_cvt_pk_bf16_f32 v98, v98, v99
	v_cvt_pk_bf16_f32 v99, v96, v97
	v_add_co_u32_e32 v96, vcc, s12, v108
	s_nop 0
	v_addc_co_u32_e32 v97, vcc, 0, v109, vcc
	global_store_dwordx2 v[96:97], v[98:99], off
	v_cvt_pk_bf16_f32 v98, v94, v95
	v_cvt_pk_bf16_f32 v99, v80, v81
	v_pk_mul_f32 v[94:95], v[94:95], v[92:93] op_sel_hi:[1,0]
	v_pk_mul_f32 v[80:81], v[80:81], v[92:93] op_sel_hi:[1,0]
	v_cvt_pk_bf16_f32 v94, v94, v95
	v_cvt_pk_bf16_f32 v95, v80, v81
	v_cvt_pk_bf16_f32 v80, v110, v111
	v_cvt_pk_bf16_f32 v81, v78, v79
	v_pk_mul_f32 v[80:81], v[110:111], v[92:93] op_sel_hi:[1,0]
	v_pk_mul_f32 v[78:79], v[78:79], v[92:93] op_sel_hi:[1,0]
	v_cvt_pk_bf16_f32 v80, v80, v81
	v_cvt_pk_bf16_f32 v81, v78, v79
	v_cvt_pk_bf16_f32 v78, v90, v91
	v_cvt_pk_bf16_f32 v79, v76, v77
	v_pk_mul_f32 v[78:79], v[90:91], v[92:93] op_sel_hi:[1,0]
	v_pk_mul_f32 v[76:77], v[76:77], v[92:93] op_sel_hi:[1,0]
	v_cvt_pk_bf16_f32 v78, v78, v79
	v_cvt_pk_bf16_f32 v79, v76, v77
	v_cvt_pk_bf16_f32 v76, v88, v89
	v_cvt_pk_bf16_f32 v77, v74, v75
	v_pk_mul_f32 v[76:77], v[88:89], v[92:93] op_sel_hi:[1,0]
	v_pk_mul_f32 v[74:75], v[74:75], v[92:93] op_sel_hi:[1,0]
	v_cvt_pk_bf16_f32 v76, v76, v77
	v_cvt_pk_bf16_f32 v77, v74, v75
	v_cvt_pk_bf16_f32 v74, v86, v87
	v_cvt_pk_bf16_f32 v75, v72, v73
	v_pk_mul_f32 v[74:75], v[86:87], v[92:93] op_sel_hi:[1,0]
	v_pk_mul_f32 v[72:73], v[72:73], v[92:93] op_sel_hi:[1,0]
	v_cvt_pk_bf16_f32 v74, v74, v75
	v_cvt_pk_bf16_f32 v75, v72, v73
	v_cvt_pk_bf16_f32 v72, v84, v85
	v_cvt_pk_bf16_f32 v73, v70, v71
	v_pk_mul_f32 v[72:73], v[84:85], v[92:93] op_sel_hi:[1,0]
	v_pk_mul_f32 v[70:71], v[70:71], v[92:93] op_sel_hi:[1,0]
	v_cvt_pk_bf16_f32 v72, v72, v73
	v_cvt_pk_bf16_f32 v73, v70, v71
	v_cvt_pk_bf16_f32 v70, v82, v83
	v_cvt_pk_bf16_f32 v71, v68, v69
	v_pk_mul_f32 v[70:71], v[82:83], v[92:93] op_sel_hi:[1,0]
	v_pk_mul_f32 v[68:69], v[68:69], v[92:93] op_sel_hi:[1,0]
	v_cvt_pk_bf16_f32 v70, v70, v71
	v_cvt_pk_bf16_f32 v71, v68, v69
	global_store_dwordx2 v[96:97], v[94:95], off offset:512
	global_store_dwordx2 v[96:97], v[80:81], off offset:1024
	global_store_dwordx2 v[96:97], v[78:79], off offset:1536
	global_store_dwordx2 v[96:97], v[76:77], off offset:2048
	global_store_dwordx2 v[96:97], v[74:75], off offset:2560
	global_store_dwordx2 v[96:97], v[72:73], off offset:3072
	global_store_dwordx2 v[96:97], v[70:71], off offset:3584
	global_store_dword v[114:115], v179, off offset:512
	s_andn2_b64 vcc, exec, s[10:11]
	v_mov_b64_e32 v[68:69], v[52:53]
	v_mov_b64_e32 v[70:71], v[54:55]
	v_mov_b64_e32 v[72:73], v[56:57]
	v_mov_b64_e32 v[74:75], v[58:59]
	v_mov_b64_e32 v[76:77], v[60:61]
	v_mov_b64_e32 v[78:79], v[62:63]
	v_mov_b64_e32 v[80:81], v[64:65]
	v_mov_b64_e32 v[98:99], v[66:67]
	v_mov_b64_e32 v[96:97], v[50:51]
	v_mov_b64_e32 v[94:95], v[48:49]
	v_mov_b64_e32 v[92:93], v[46:47]
	v_mov_b64_e32 v[90:91], v[44:45]
	v_mov_b64_e32 v[88:89], v[42:43]
	v_mov_b64_e32 v[86:87], v[40:41]
	v_mov_b64_e32 v[84:85], v[38:39]
	v_mov_b64_e32 v[82:83], v[36:37]
	v_mov_b32_e32 v180, v181
	s_cbranch_vccz .LBB0_2009
.LBB0_2007:
	s_add_i32 s0, s0, s94
	s_cmpk_gt_i32 s0, 0x407f
	s_cselect_b64 s[10:11], -1, 0
	s_and_b64 vcc, exec, s[10:11]
	s_cbranch_vccnz .LBB0_2006
	v_lshl_add_u64 v[52:53], s[8:9], 0, v[34:35]
	v_add_co_u32_e32 v178, vcc, 0x2f883000, v52
	s_nop 1
	v_addc_co_u32_e32 v179, vcc, 0, v53, vcc
	global_load_dword v181, v[178:179], off offset:0
	v_add_co_u32_e32 v54, vcc, 0x2b783000, v52
	s_nop 1
	v_addc_co_u32_e32 v55, vcc, 0, v53, vcc
	v_add_co_u32_e32 v108, vcc, 0xc803000, v52
	global_load_dwordx2 v[50:51], v[54:55], off
	global_load_dwordx2 v[48:49], v[54:55], off offset:512
	global_load_dwordx2 v[46:47], v[54:55], off offset:1024
	global_load_dwordx2 v[44:45], v[54:55], off offset:1536
	global_load_dwordx2 v[42:43], v[54:55], off offset:2048
	global_load_dwordx2 v[40:41], v[54:55], off offset:2560
	global_load_dwordx2 v[38:39], v[54:55], off offset:3072
	global_load_dwordx2 v[36:37], v[54:55], off offset:3584
	v_addc_co_u32_e32 v109, vcc, 0, v53, vcc
	global_load_dwordx2 v[66:67], v[108:109], off
	global_load_dwordx2 v[64:65], v[108:109], off offset:512
	global_load_dwordx2 v[62:63], v[108:109], off offset:1024
	global_load_dwordx2 v[60:61], v[108:109], off offset:1536
	global_load_dwordx2 v[58:59], v[108:109], off offset:2048
	global_load_dwordx2 v[56:57], v[108:109], off offset:2560
	global_load_dwordx2 v[54:55], v[108:109], off offset:3072
	global_load_dwordx2 v[52:53], v[108:109], off offset:3584
	s_branch .LBB0_2006

.LBB0_4602:
	s_or_b64 exec, exec, s[0:1]
	s_mov_b64 s[4:5], s[84:85]
	s_waitcnt lgkmcnt(0)
	v_mov_b32_e32 v1, v0
	v_readlane_b32 s0, v254, 9
	s_barrier
	v_readlane_b32 s1, v254, 10
	s_add_i32 s0, s0, s1
	s_cmpk_gt_i32 s0, 0x407f
	s_cbranch_scc1 .LBB0_4607
	s_load_dwordx2 s[6:7], s[4:5], 0x48
	s_load_dwordx2 s[8:9], s[4:5], 0xd0
	v_and_b32_e32 v1, 63, v1
	v_lshlrev_b32_e32 v26, 4, v1
	v_or_b32_e32 v10, 0x400, v26
	s_waitcnt lgkmcnt(0)
	s_add_u32 s4, s6, 0xa000
	s_addc_u32 s5, s7, 0
	v_or_b32_e32 v18, 0x800, v26
	v_or_b32_e32 v19, 0xc00, v26
	v_or_b32_e32 v27, 0x1000, v26
	v_or_b32_e32 v28, 0x1400, v26
	v_or_b32_e32 v34, 0x1800, v26
	s_ashr_i32 s1, s0, 31
	global_load_dwordx4 v[2:5], v26, s[4:5]
	global_load_dwordx4 v[6:9], v10, s[4:5]
	s_nop 0
	global_load_dwordx4 v[10:13], v18, s[4:5]
	global_load_dwordx4 v[14:17], v19, s[4:5]
	s_nop 0
	global_load_dwordx4 v[18:21], v27, s[4:5]
	global_load_dwordx4 v[22:25], v28, s[4:5]
	v_or_b32_e32 v35, 0x1c00, v26
	global_load_dwordx4 v[26:29], v34, s[4:5]
	global_load_dwordx4 v[30:33], v35, s[4:5]
	s_lshl_b64 s[4:5], s[0:1], 12
	s_add_u32 s4, s8, s4
	v_lshlrev_b32_e32 v34, 3, v1
	v_mov_b32_e32 v35, 0
	s_addc_u32 s5, s9, s5
	v_lshl_add_u64 v[36:37], s[4:5], 0, v[34:35]
	v_add_co_u32_e32 v178, vcc, 0x2f883000, v36
	s_nop 1
	v_addc_co_u32_e32 v179, vcc, 0, v37, vcc
	global_load_dword v180, v[178:179], off offset:512
	s_mov_b32 s1, 0x2b783000
	s_mov_b64 s[6:7], 0x2b783000
	v_add_co_u32_e32 v40, vcc, s1, v36
	v_lshl_add_u64 v[38:39], v[36:37], 0, s[6:7]
	s_nop 0
	v_addc_co_u32_e32 v41, vcc, 0, v37, vcc
	s_mov_b64 s[6:7], 0xc803000
	s_mov_b32 s1, 0xc803000
	global_load_dwordx2 v[94:95], v[38:39], off offset:512
	global_load_dwordx2 v[92:93], v[38:39], off offset:1024
	global_load_dwordx2 v[90:91], v[38:39], off offset:1536
	global_load_dwordx2 v[88:89], v[38:39], off offset:2048
	global_load_dwordx2 v[96:97], v[40:41], off
	global_load_dwordx2 v[86:87], v[38:39], off offset:2560
	global_load_dwordx2 v[84:85], v[38:39], off offset:3072
	global_load_dwordx2 v[82:83], v[38:39], off offset:3584
	v_lshl_add_u64 v[38:39], v[36:37], 0, s[6:7]
	v_add_co_u32_e32 v36, vcc, s1, v36
	v_mbcnt_lo_u32_b32 v1, -1, 0
	s_nop 0
	v_addc_co_u32_e32 v37, vcc, 0, v37, vcc
	global_load_dwordx2 v[80:81], v[38:39], off offset:512
	global_load_dwordx2 v[78:79], v[38:39], off offset:1024
	global_load_dwordx2 v[76:77], v[38:39], off offset:1536
	global_load_dwordx2 v[74:75], v[38:39], off offset:2048
	global_load_dwordx2 v[98:99], v[36:37], off
	global_load_dwordx2 v[72:73], v[38:39], off offset:2560
	global_load_dwordx2 v[70:71], v[38:39], off offset:3072
	global_load_dwordx2 v[68:69], v[38:39], off offset:3584
	v_mbcnt_hi_u32_b32 v36, -1, v1
	v_and_b32_e32 v1, 64, v36
	v_add_u32_e32 v37, 64, v1
	v_xor_b32_e32 v1, 1, v36
	v_cmp_lt_i32_e32 vcc, v1, v37
	v_xor_b32_e32 v38, 2, v36
	s_add_i32 s10, s0, s94
	v_cndmask_b32_e32 v1, v36, v1, vcc
	v_cmp_lt_i32_e32 vcc, v38, v37
	s_ashr_i32 s95, s94, 31
	s_ashr_i32 s11, s10, 31
	v_cndmask_b32_e32 v38, v36, v38, vcc
	v_lshlrev_b32_e32 v100, 2, v38
	v_xor_b32_e32 v38, 4, v36
	v_cmp_lt_i32_e32 vcc, v38, v37
	s_lshl_b64 s[6:7], s[94:95], 12
	s_lshl_b64 s[10:11], s[10:11], 12
	v_cndmask_b32_e32 v38, v36, v38, vcc
	v_lshlrev_b32_e32 v101, 2, v38
	v_xor_b32_e32 v38, 8, v36
	v_cmp_lt_i32_e32 vcc, v38, v37
	s_add_u32 s8, s8, s10
	v_lshlrev_b32_e32 v1, 2, v1
	v_cndmask_b32_e32 v38, v36, v38, vcc
	v_lshlrev_b32_e32 v102, 2, v38
	v_xor_b32_e32 v38, 16, v36
	v_cmp_lt_i32_e32 vcc, v38, v37
	s_addc_u32 s9, s9, s11
	v_mov_b32_e32 v105, 0x358637bd
	v_cndmask_b32_e32 v38, v36, v38, vcc
	v_lshlrev_b32_e32 v103, 2, v38
	v_xor_b32_e32 v38, 32, v36
	v_cmp_lt_i32_e32 vcc, v38, v37
	s_mov_b32 s3, 0x800000
	s_mov_b32 s12, 0xc803000
	v_cndmask_b32_e32 v36, v36, v38, vcc
	v_lshlrev_b32_e32 v104, 2, v36
	s_branch .LBB0_4605
.LBB0_4604:
	s_waitcnt vmcnt(11)
	v_lshlrev_b32_e32 v108, 16, v96
	v_and_b32_e32 v109, 0xffff0000, v96
	v_lshlrev_b32_e32 v96, 16, v97
	v_and_b32_e32 v97, 0xffff0000, v97
	v_mul_f32_e32 v110, v97, v97
	v_lshlrev_b32_e32 v115, 16, v95
	v_lshlrev_b32_e32 v114, 16, v94
	v_and_b32_e32 v95, 0xffff0000, v95
	v_and_b32_e32 v94, 0xffff0000, v94
	v_lshlrev_b32_e32 v121, 16, v90
	v_mul_f32_e32 v120, v109, v109
	v_pk_fma_f32 v[110:111], v[96:97], v[96:97], v[110:111] op_sel_hi:[1,1,0]
	v_pk_mul_f32 v[116:117], v[94:95], v[94:95]
	v_pk_fma_f32 v[124:125], v[108:109], v[108:109], v[120:121] op_sel_hi:[1,1,0]
	v_pk_fma_f32 v[116:117], v[114:115], v[114:115], v[116:117]
	v_and_b32_e32 v123, 0xffff0000, v90
	v_mov_b32_e32 v120, v124
	v_mov_b32_e32 v126, v110
	v_mov_b32_e32 v127, v121
	v_mul_f32_e32 v113, v123, v123
	v_pk_add_f32 v[110:111], v[124:125], v[110:111]
	v_pk_mul_f32 v[124:125], v[120:121], v[126:127]
	v_pk_add_f32 v[116:117], v[116:117], v[116:117] op_sel:[0,1] op_sel_hi:[1,0]
	v_lshlrev_b32_e32 v118, 16, v92
	v_and_b32_e32 v119, 0xffff0000, v92
	v_lshlrev_b32_e32 v92, 16, v93
	v_and_b32_e32 v93, 0xffff0000, v93
	v_mov_b32_e32 v111, v125
	v_mov_b32_e32 v117, v113
	v_lshlrev_b32_e32 v90, 16, v91
	v_and_b32_e32 v91, 0xffff0000, v91
	v_pk_add_f32 v[110:111], v[110:111], v[116:117]
	v_mul_f32_e32 v116, v119, v119
	v_mul_f32_e32 v120, v93, v93
	v_mul_f32_e32 v122, v90, v90
	v_mul_f32_e32 v128, v91, v91
	v_pk_fma_f32 v[116:117], v[118:119], v[118:119], v[116:117] op_sel_hi:[1,1,0]
	v_pk_fma_f32 v[124:125], v[92:93], v[92:93], v[120:121] op_sel_hi:[1,1,0]
	v_mov_b32_e32 v117, v122
	v_mov_b32_e32 v125, v128
	v_pk_add_f32 v[116:117], v[116:117], v[124:125]
	s_waitcnt vmcnt(10)
	v_lshlrev_b32_e32 v127, 16, v87
	v_pk_add_f32 v[110:111], v[110:111], v[116:117]
	v_lshlrev_b32_e32 v117, 16, v89
	v_lshlrev_b32_e32 v116, 16, v88
	v_and_b32_e32 v89, 0xffff0000, v89
	v_and_b32_e32 v88, 0xffff0000, v88
	v_pk_mul_f32 v[124:125], v[88:89], v[88:89]
	v_lshlrev_b32_e32 v126, 16, v86
	v_pk_fma_f32 v[124:125], v[116:117], v[116:117], v[124:125]
	v_and_b32_e32 v87, 0xffff0000, v87
	v_pk_add_f32 v[124:125], v[124:125], v[124:125] op_sel:[0,1] op_sel_hi:[1,0]
	v_and_b32_e32 v86, 0xffff0000, v86
	s_waitcnt vmcnt(8)
	v_lshlrev_b32_e32 v133, 16, v82
	v_pk_add_f32 v[110:111], v[110:111], v[110:111] op_sel:[0,1] op_sel_hi:[1,0]
	v_pk_mul_f32 v[128:129], v[86:87], v[86:87]
	v_mov_b32_e32 v132, v110
	v_mov_b32_e32 v136, v124
	v_mov_b32_e32 v137, v133
	v_pk_fma_f32 v[128:129], v[126:127], v[126:127], v[128:129]
	v_and_b32_e32 v135, 0xffff0000, v82
	v_pk_add_f32 v[110:111], v[110:111], v[124:125]
	v_pk_mul_f32 v[124:125], v[132:133], v[136:137]
	v_and_b32_e32 v131, 0xffff0000, v84
	v_mul_f32_e32 v113, v135, v135
	v_mov_b32_e32 v111, v125
	v_pk_add_f32 v[124:125], v[128:129], v[128:129] op_sel:[0,1] op_sel_hi:[1,0]
	v_lshlrev_b32_e32 v130, 16, v84
	v_lshlrev_b32_e32 v84, 16, v85
	v_and_b32_e32 v85, 0xffff0000, v85
	v_mov_b32_e32 v125, v113
	v_mul_f32_e32 v120, v131, v131
	v_lshlrev_b32_e32 v82, 16, v83
	v_and_b32_e32 v83, 0xffff0000, v83
	v_pk_add_f32 v[110:111], v[110:111], v[124:125]
	v_pk_fma_f32 v[124:125], v[130:131], v[130:131], v[120:121] op_sel_hi:[1,1,0]
	v_mul_f32_e32 v120, v85, v85
	v_mul_f32_e32 v122, v82, v82
	v_mul_f32_e32 v134, v83, v83
	v_pk_fma_f32 v[128:129], v[84:85], v[84:85], v[120:121] op_sel_hi:[1,1,0]
	v_mov_b32_e32 v125, v122
	v_mov_b32_e32 v129, v134
	v_pk_add_f32 v[124:125], v[124:125], v[128:129]
	s_waitcnt vmcnt(3)
	v_lshlrev_b32_e32 v106, 16, v98
	v_mul_f32_e32 v106, v180, v106
	v_pk_add_f32 v[110:111], v[110:111], v[124:125]
	v_and_b32_e32 v107, 0xffff0000, v98
	v_mul_f32_e32 v107, v180, v107
	v_add_f32_e32 v111, v110, v111
	ds_bpermute_b32 v120, v1, v111
	v_lshlrev_b32_e32 v98, 16, v99
	v_mul_f32_e32 v98, v180, v98
	v_and_b32_e32 v99, 0xffff0000, v99
	v_mul_f32_e32 v99, v180, v99
	v_lshlrev_b32_e32 v112, 16, v80
	v_mul_f32_e32 v112, v180, v112
	v_and_b32_e32 v113, 0xffff0000, v80
	v_mul_f32_e32 v113, v180, v113
	s_waitcnt lgkmcnt(0)
	v_add_f32_e32 v120, v111, v120
	ds_bpermute_b32 v122, v100, v120
	v_lshlrev_b32_e32 v80, 16, v81
	v_mul_f32_e32 v80, v180, v80
	v_and_b32_e32 v81, 0xffff0000, v81
	v_mul_f32_e32 v81, v180, v81
	v_lshlrev_b32_e32 v110, 16, v78
	v_mul_f32_e32 v110, v180, v110
	v_and_b32_e32 v111, 0xffff0000, v78
	v_mul_f32_e32 v111, v180, v111
	s_waitcnt lgkmcnt(0)
	v_add_f32_e32 v120, v120, v122
	ds_bpermute_b32 v122, v101, v120
	v_lshlrev_b32_e32 v78, 16, v79
	v_mul_f32_e32 v78, v180, v78
	v_and_b32_e32 v79, 0xffff0000, v79
	v_mul_f32_e32 v79, v180, v79
	v_lshlrev_b32_e32 v124, 16, v76
	v_mul_f32_e32 v124, v180, v124
	v_and_b32_e32 v125, 0xffff0000, v76
	v_mul_f32_e32 v125, v180, v125
	s_waitcnt lgkmcnt(0)
	v_add_f32_e32 v120, v120, v122
	ds_bpermute_b32 v122, v102, v120
	v_lshlrev_b32_e32 v76, 16, v77
	v_mul_f32_e32 v76, v180, v76
	v_and_b32_e32 v77, 0xffff0000, v77
	v_mul_f32_e32 v77, v180, v77
	v_lshlrev_b32_e32 v128, 16, v74
	v_mul_f32_e32 v128, v180, v128
	v_and_b32_e32 v129, 0xffff0000, v74
	v_mul_f32_e32 v129, v180, v129
	s_waitcnt lgkmcnt(0)
	v_add_f32_e32 v120, v120, v122
	ds_bpermute_b32 v122, v103, v120
	v_lshlrev_b32_e32 v74, 16, v75
	v_mul_f32_e32 v74, v180, v74
	v_and_b32_e32 v75, 0xffff0000, v75
	v_mul_f32_e32 v75, v180, v75
	s_waitcnt vmcnt(2)
	v_lshlrev_b32_e32 v136, 16, v72
	v_mul_f32_e32 v136, v180, v136
	v_and_b32_e32 v137, 0xffff0000, v72
	v_mul_f32_e32 v137, v180, v137
	s_waitcnt lgkmcnt(0)
	v_add_f32_e32 v120, v120, v122
	ds_bpermute_b32 v122, v104, v120
	v_lshlrev_b32_e32 v72, 16, v73
	v_mul_f32_e32 v72, v180, v72
	v_and_b32_e32 v73, 0xffff0000, v73
	v_mul_f32_e32 v73, v180, v73
	s_waitcnt vmcnt(1)
	v_lshlrev_b32_e32 v138, 16, v70
	v_mul_f32_e32 v138, v180, v138
	v_and_b32_e32 v139, 0xffff0000, v70
	v_mul_f32_e32 v139, v180, v139
	s_waitcnt lgkmcnt(0)
	v_add_f32_e32 v120, v120, v122
	v_fmamk_f32 v120, v120, 0x3a000000, v105
	v_mul_f32_e32 v122, 0x4b800000, v120
	v_cmp_gt_f32_e32 vcc, s3, v120
	v_lshlrev_b32_e32 v70, 16, v71
	v_mul_f32_e32 v70, v180, v70
	v_and_b32_e32 v71, 0xffff0000, v71
	v_mul_f32_e32 v71, v180, v71
	v_cndmask_b32_e32 v120, v120, v122, vcc
	v_rsq_f32_e32 v120, v120
	v_mov_b32_e32 v134, v133
	s_waitcnt vmcnt(0)
	v_lshlrev_b32_e32 v140, 16, v68
	v_mul_f32_e32 v140, v180, v140
	v_and_b32_e32 v141, 0xffff0000, v68
	v_mul_f32_e32 v141, v180, v141
	v_mul_f32_e32 v122, 0x45800000, v120
	v_cndmask_b32_e32 v120, v120, v122, vcc
	v_pk_mul_f32 v[108:109], v[120:121], v[108:109] op_sel_hi:[0,1]
	v_pk_mul_f32 v[96:97], v[120:121], v[96:97] op_sel_hi:[0,1]
	v_pk_fma_f32 v[96:97], v[4:5], v[96:97], v[98:99]
	v_pk_fma_f32 v[98:99], v[2:3], v[108:109], v[106:107]
	v_mov_b32_e32 v106, v114
	v_mov_b32_e32 v107, v94
	v_mov_b32_e32 v94, v115
	v_pk_mul_f32 v[106:107], v[120:121], v[106:107] op_sel_hi:[0,1]
	v_pk_mul_f32 v[94:95], v[120:121], v[94:95] op_sel_hi:[0,1]
	v_pk_fma_f32 v[80:81], v[8:9], v[94:95], v[80:81]
	v_pk_fma_f32 v[94:95], v[6:7], v[106:107], v[112:113]
	v_mov_b32_e32 v108, v99
	v_mov_b32_e32 v109, v95
	v_mov_b32_e32 v106, v98
	v_mov_b32_e32 v107, v94
	v_pk_mul_f32 v[108:109], v[108:109], v[108:109]
	v_mov_b32_e32 v112, v97
	v_mov_b32_e32 v113, v81
	v_pk_fma_f32 v[106:107], v[106:107], v[106:107], v[108:109]
	v_mov_b32_e32 v108, v96
	v_mov_b32_e32 v109, v80
	v_pk_mul_f32 v[112:113], v[112:113], v[112:113]
	v_pk_mul_f32 v[92:93], v[120:121], v[92:93] op_sel_hi:[0,1]
	v_pk_fma_f32 v[108:109], v[108:109], v[108:109], v[112:113]
	v_pk_fma_f32 v[78:79], v[12:13], v[92:93], v[78:79]
	v_pk_add_f32 v[106:107], v[106:107], v[108:109]
	v_pk_mul_f32 v[108:109], v[120:121], v[118:119] op_sel_hi:[0,1]
	v_pk_fma_f32 v[108:109], v[10:11], v[108:109], v[110:111]
	v_pk_mul_f32 v[92:93], v[78:79], v[78:79]
	v_pk_mul_f32 v[110:111], v[108:109], v[108:109]
	v_mov_b32_e32 v122, v121
	v_pk_mov_b32 v[112:113], v[110:111], v[92:93] op_sel:[1,0]
	v_mov_b32_e32 v111, v93
	v_pk_add_f32 v[92:93], v[112:113], v[110:111]
	v_pk_mul_f32 v[110:111], v[122:123], v[120:121] op_sel_hi:[1,0]
	v_pk_mul_f32 v[90:91], v[90:91], v[120:121] op_sel_hi:[1,0]
	v_pk_add_f32 v[92:93], v[92:93], v[92:93] op_sel_hi:[0,1]
	v_pk_fma_f32 v[76:77], v[16:17], v[90:91], v[76:77]
	v_pk_fma_f32 v[90:91], v[14:15], v[110:111], v[124:125]
	v_mov_b32_e32 v115, v88
	v_mov_b32_e32 v88, v117
	v_mul_f32_e32 v92, v90, v90
	v_pk_mul_f32 v[88:89], v[120:121], v[88:89] op_sel_hi:[0,1]
	v_pk_add_f32 v[106:107], v[106:107], v[106:107] op_sel_hi:[0,1]
	v_pk_fma_f32 v[110:111], v[90:91], v[90:91], v[92:93] op_sel_hi:[1,1,0]
	v_mul_f32_e32 v92, v76, v76
	v_mov_b32_e32 v114, v116
	v_pk_fma_f32 v[74:75], v[20:21], v[88:89], v[74:75]
	v_pk_fma_f32 v[112:113], v[76:77], v[76:77], v[92:93] op_sel_hi:[1,1,0]
	v_pk_mul_f32 v[114:115], v[120:121], v[114:115] op_sel_hi:[0,1]
	v_mul_f32_e32 v92, v74, v74
	v_mul_f32_e32 v106, v75, v75
	v_pk_fma_f32 v[88:89], v[18:19], v[114:115], v[128:129]
	v_pk_add_f32 v[92:93], v[92:93], v[106:107]
	v_mov_b32_e32 v106, v127
	v_mov_b32_e32 v107, v87
	v_mov_b32_e32 v127, v86
	v_mul_f32_e32 v110, v88, v88
	v_mul_f32_e32 v112, v89, v89
	v_pk_mul_f32 v[106:107], v[120:121], v[106:107] op_sel_hi:[0,1]
	v_pk_mul_f32 v[86:87], v[120:121], v[126:127] op_sel_hi:[0,1]
	v_pk_add_f32 v[110:111], v[110:111], v[112:113]
	v_pk_fma_f32 v[86:87], v[22:23], v[86:87], v[136:137]
	v_pk_fma_f32 v[72:73], v[24:25], v[106:107], v[72:73]
	v_pk_add_f32 v[92:93], v[110:111], v[92:93]
	v_pk_mul_f32 v[106:107], v[72:73], v[72:73]
	v_pk_mul_f32 v[110:111], v[86:87], v[86:87]
	v_pk_mul_f32 v[84:85], v[120:121], v[84:85] op_sel_hi:[0,1]
	v_pk_mov_b32 v[112:113], v[110:111], v[106:107] op_sel:[1,0]
	v_mov_b32_e32 v111, v107
	v_pk_add_f32 v[106:107], v[112:113], v[110:111]
	v_pk_mul_f32 v[110:111], v[120:121], v[130:131] op_sel_hi:[0,1]
	v_pk_add_f32 v[92:93], v[92:93], v[92:93] op_sel_hi:[0,1]
	v_pk_fma_f32 v[70:71], v[28:29], v[84:85], v[70:71]
	v_pk_fma_f32 v[84:85], v[26:27], v[110:111], v[138:139]
	v_lshlrev_b32_e32 v68, 16, v69
	v_mul_f32_e32 v68, v180, v68
	v_mul_f32_e32 v92, v84, v84
	v_and_b32_e32 v69, 0xffff0000, v69
	v_mul_f32_e32 v69, v180, v69
	v_pk_fma_f32 v[110:111], v[84:85], v[84:85], v[92:93] op_sel_hi:[1,1,0]
	v_mul_f32_e32 v92, v70, v70
	v_pk_mul_f32 v[114:115], v[134:135], v[120:121] op_sel_hi:[1,0]
	v_pk_mul_f32 v[82:83], v[82:83], v[120:121] op_sel_hi:[1,0]
	v_pk_add_f32 v[106:107], v[106:107], v[106:107] op_sel_hi:[0,1]
	v_pk_fma_f32 v[112:113], v[70:71], v[70:71], v[92:93] op_sel_hi:[1,1,0]
	v_pk_fma_f32 v[68:69], v[32:33], v[82:83], v[68:69]
	v_pk_fma_f32 v[82:83], v[30:31], v[114:115], v[140:141]
	v_mul_f32_e32 v106, v68, v68
	v_mul_f32_e32 v110, v82, v82
	v_mul_f32_e32 v112, v83, v83
	v_mul_f32_e32 v92, v69, v69
	v_pk_add_f32 v[110:111], v[110:111], v[112:113]
	v_pk_add_f32 v[92:93], v[106:107], v[92:93]
	v_lshl_add_u64 v[106:107], s[4:5], 0, v[34:35]
	v_pk_add_f32 v[92:93], v[110:111], v[92:93]
	v_cvt_pk_bf16_f32 v110, v98, v99
	v_add_f32_e32 v92, v92, v93
	ds_bpermute_b32 v93, v1, v92
	v_cvt_pk_bf16_f32 v111, v96, v97
	s_add_u32 s4, s4, s6
	s_addc_u32 s5, s5, s7
	s_add_u32 s8, s8, s6
	s_waitcnt lgkmcnt(0)
	v_add_f32_e32 v92, v92, v93
	ds_bpermute_b32 v93, v100, v92
	s_addc_u32 s9, s9, s7
	s_waitcnt lgkmcnt(0)
	v_add_f32_e32 v92, v92, v93
	ds_bpermute_b32 v93, v101, v92
	s_waitcnt lgkmcnt(0)
	v_add_f32_e32 v92, v92, v93
	ds_bpermute_b32 v93, v102, v92
	s_waitcnt lgkmcnt(0)
	v_add_f32_e32 v92, v92, v93
	ds_bpermute_b32 v93, v103, v92
	s_waitcnt lgkmcnt(0)
	v_add_f32_e32 v92, v92, v93
	ds_bpermute_b32 v93, v104, v92
	s_waitcnt lgkmcnt(0)
	v_add_f32_e32 v92, v92, v93
	v_fmamk_f32 v92, v92, 0x3a000000, v105
	v_mul_f32_e32 v93, 0x4b800000, v92
	v_cmp_gt_f32_e32 vcc, s3, v92
	s_nop 1
	v_cndmask_b32_e32 v92, v92, v93, vcc
	v_rsq_f32_e32 v92, v92
	s_nop 0
	v_mul_f32_e32 v93, 0x45800000, v92
	v_cndmask_b32_e32 v92, v92, v93, vcc
	v_rcp_f32_e32 v179, v92
	v_add_co_u32_e32 v112, vcc, 0x2f883000, v106
	v_pk_mul_f32 v[98:99], v[98:99], v[92:93] op_sel_hi:[1,0]
	s_nop 0
	v_addc_co_u32_e32 v113, vcc, 0, v107, vcc
	v_pk_mul_f32 v[96:97], v[96:97], v[92:93] op_sel_hi:[1,0]
	v_cvt_pk_bf16_f32 v98, v98, v99
	v_cvt_pk_bf16_f32 v99, v96, v97
	v_add_co_u32_e32 v96, vcc, s12, v106
	s_nop 0
	v_addc_co_u32_e32 v97, vcc, 0, v107, vcc
	global_store_dwordx2 v[96:97], v[98:99], off
	v_cvt_pk_bf16_f32 v98, v94, v95
	v_cvt_pk_bf16_f32 v99, v80, v81
	v_pk_mul_f32 v[94:95], v[94:95], v[92:93] op_sel_hi:[1,0]
	v_pk_mul_f32 v[80:81], v[80:81], v[92:93] op_sel_hi:[1,0]
	v_cvt_pk_bf16_f32 v94, v94, v95
	v_cvt_pk_bf16_f32 v95, v80, v81
	v_cvt_pk_bf16_f32 v80, v108, v109
	v_cvt_pk_bf16_f32 v81, v78, v79
	v_pk_mul_f32 v[80:81], v[108:109], v[92:93] op_sel_hi:[1,0]
	v_pk_mul_f32 v[78:79], v[78:79], v[92:93] op_sel_hi:[1,0]
	v_cvt_pk_bf16_f32 v80, v80, v81
	v_cvt_pk_bf16_f32 v81, v78, v79
	v_cvt_pk_bf16_f32 v78, v90, v91
	v_cvt_pk_bf16_f32 v79, v76, v77
	v_pk_mul_f32 v[78:79], v[90:91], v[92:93] op_sel_hi:[1,0]
	v_pk_mul_f32 v[76:77], v[76:77], v[92:93] op_sel_hi:[1,0]
	v_cvt_pk_bf16_f32 v78, v78, v79
	v_cvt_pk_bf16_f32 v79, v76, v77
	v_cvt_pk_bf16_f32 v76, v88, v89
	v_cvt_pk_bf16_f32 v77, v74, v75
	v_pk_mul_f32 v[76:77], v[88:89], v[92:93] op_sel_hi:[1,0]
	v_pk_mul_f32 v[74:75], v[74:75], v[92:93] op_sel_hi:[1,0]
	v_cvt_pk_bf16_f32 v76, v76, v77
	v_cvt_pk_bf16_f32 v77, v74, v75
	v_cvt_pk_bf16_f32 v74, v86, v87
	v_cvt_pk_bf16_f32 v75, v72, v73
	v_pk_mul_f32 v[74:75], v[86:87], v[92:93] op_sel_hi:[1,0]
	v_pk_mul_f32 v[72:73], v[72:73], v[92:93] op_sel_hi:[1,0]
	v_cvt_pk_bf16_f32 v74, v74, v75
	v_cvt_pk_bf16_f32 v75, v72, v73
	v_cvt_pk_bf16_f32 v72, v84, v85
	v_cvt_pk_bf16_f32 v73, v70, v71
	v_pk_mul_f32 v[72:73], v[84:85], v[92:93] op_sel_hi:[1,0]
	v_pk_mul_f32 v[70:71], v[70:71], v[92:93] op_sel_hi:[1,0]
	v_cvt_pk_bf16_f32 v72, v72, v73
	v_cvt_pk_bf16_f32 v73, v70, v71
	v_cvt_pk_bf16_f32 v70, v82, v83
	v_cvt_pk_bf16_f32 v71, v68, v69
	v_pk_mul_f32 v[70:71], v[82:83], v[92:93] op_sel_hi:[1,0]
	v_pk_mul_f32 v[68:69], v[68:69], v[92:93] op_sel_hi:[1,0]
	v_cvt_pk_bf16_f32 v70, v70, v71
	v_cvt_pk_bf16_f32 v71, v68, v69
	global_store_dwordx2 v[96:97], v[94:95], off offset:512
	global_store_dwordx2 v[96:97], v[80:81], off offset:1024
	global_store_dwordx2 v[96:97], v[78:79], off offset:1536
	global_store_dwordx2 v[96:97], v[76:77], off offset:2048
	global_store_dwordx2 v[96:97], v[74:75], off offset:2560
	global_store_dwordx2 v[96:97], v[72:73], off offset:3072
	global_store_dwordx2 v[96:97], v[70:71], off offset:3584
	global_store_dword v[112:113], v179, off offset:1024
	s_andn2_b64 vcc, exec, s[10:11]
	v_mov_b64_e32 v[68:69], v[52:53]
	v_mov_b64_e32 v[70:71], v[54:55]
	v_mov_b64_e32 v[72:73], v[56:57]
	v_mov_b64_e32 v[74:75], v[58:59]
	v_mov_b64_e32 v[76:77], v[60:61]
	v_mov_b64_e32 v[78:79], v[62:63]
	v_mov_b64_e32 v[80:81], v[64:65]
	v_mov_b64_e32 v[98:99], v[66:67]
	v_mov_b64_e32 v[96:97], v[50:51]
	v_mov_b64_e32 v[94:95], v[48:49]
	v_mov_b64_e32 v[92:93], v[46:47]
	v_mov_b64_e32 v[90:91], v[44:45]
	v_mov_b64_e32 v[88:89], v[42:43]
	v_mov_b64_e32 v[86:87], v[40:41]
	v_mov_b64_e32 v[84:85], v[38:39]
	v_mov_b64_e32 v[82:83], v[36:37]
	v_mov_b32_e32 v180, v181
	s_cbranch_vccz .LBB0_4607
.LBB0_4605:
	s_add_i32 s0, s0, s94
	s_cmpk_gt_i32 s0, 0x407f
	s_cselect_b64 s[10:11], -1, 0
	s_and_b64 vcc, exec, s[10:11]
	s_cbranch_vccnz .LBB0_4604
	v_lshl_add_u64 v[52:53], s[8:9], 0, v[34:35]
	v_add_co_u32_e32 v178, vcc, 0x2f883000, v52
	s_nop 1
	v_addc_co_u32_e32 v179, vcc, 0, v53, vcc
	global_load_dword v181, v[178:179], off offset:512
	v_add_co_u32_e32 v54, vcc, 0x2b783000, v52
	s_nop 1
	v_addc_co_u32_e32 v55, vcc, 0, v53, vcc
	v_add_co_u32_e32 v106, vcc, 0xc803000, v52
	global_load_dwordx2 v[50:51], v[54:55], off
	global_load_dwordx2 v[48:49], v[54:55], off offset:512
	global_load_dwordx2 v[46:47], v[54:55], off offset:1024
	global_load_dwordx2 v[44:45], v[54:55], off offset:1536
	global_load_dwordx2 v[42:43], v[54:55], off offset:2048
	global_load_dwordx2 v[40:41], v[54:55], off offset:2560
	global_load_dwordx2 v[38:39], v[54:55], off offset:3072
	global_load_dwordx2 v[36:37], v[54:55], off offset:3584
	v_addc_co_u32_e32 v107, vcc, 0, v53, vcc
	global_load_dwordx2 v[66:67], v[106:107], off
	global_load_dwordx2 v[64:65], v[106:107], off offset:512
	global_load_dwordx2 v[62:63], v[106:107], off offset:1024
	global_load_dwordx2 v[60:61], v[106:107], off offset:1536
	global_load_dwordx2 v[58:59], v[106:107], off offset:2048
	global_load_dwordx2 v[56:57], v[106:107], off offset:2560
	global_load_dwordx2 v[54:55], v[106:107], off offset:3072
	global_load_dwordx2 v[52:53], v[106:107], off offset:3584
	s_branch .LBB0_4604

.LBB0_4911:
	s_or_b64 exec, exec, s[0:1]
	v_readlane_b32 s0, v254, 9
	s_waitcnt lgkmcnt(0)
	s_barrier
	v_readlane_b32 s1, v254, 10
	s_add_i32 s0, s0, s1
	s_cmpk_gt_i32 s0, 0x407f
	s_cbranch_scc1 .LBB0_4916
	s_load_dwordx2 s[2:3], s[84:85], 0x48
	s_load_dwordx4 s[4:7], s[84:85], 0xc8
	v_and_b32_e32 v34, 63, v0
	v_lshlrev_b32_e32 v8, 4, v34
	v_or_b32_e32 v36, 0x100, v34
	s_waitcnt lgkmcnt(0)
	s_add_u32 s2, s2, 0xe000
	v_or_b32_e32 v38, 0x140, v34
	v_or_b32_e32 v40, 0x180, v34
	s_addc_u32 s3, s3, 0
	v_or_b32_e32 v9, 0x400, v8
	v_or_b32_e32 v16, 0x800, v8
	v_or_b32_e32 v17, 0xc00, v8
	v_lshlrev_b32_e32 v24, 4, v36
	v_lshlrev_b32_e32 v25, 4, v38
	v_lshlrev_b32_e32 v32, 4, v40
	v_or_b32_e32 v42, 0x1c0, v34
	s_ashr_i32 s1, s0, 31
	global_load_dwordx4 v[0:3], v8, s[2:3]
	global_load_dwordx4 v[4:7], v9, s[2:3]
	s_nop 0
	global_load_dwordx4 v[8:11], v16, s[2:3]
	global_load_dwordx4 v[12:15], v17, s[2:3]
	s_nop 0
	global_load_dwordx4 v[16:19], v24, s[2:3]
	global_load_dwordx4 v[20:23], v25, s[2:3]
	v_lshlrev_b32_e32 v35, 4, v42
	global_load_dwordx4 v[24:27], v32, s[2:3]
	global_load_dwordx4 v[28:31], v35, s[2:3]
	s_lshl_b64 s[2:3], s[0:1], 12
	s_add_u32 s2, s6, s2
	v_mov_b32_e32 v33, 0
	v_lshlrev_b32_e32 v32, 3, v34
	s_addc_u32 s3, s7, s3
	v_lshl_add_u64 v[44:45], s[2:3], 0, v[32:33]
	v_add_co_u32_e32 v178, vcc, 0x2f883000, v44
	s_nop 1
	v_addc_co_u32_e32 v179, vcc, 0, v45, vcc
	global_load_dword v180, v[178:179], off offset:1024
	s_mov_b64 s[2:3], 0x2b783000
	v_lshl_add_u64 v[46:47], v[44:45], 0, s[2:3]
	s_mov_b32 s2, 0x2b783000
	v_add_co_u32_e32 v48, vcc, s2, v44
	s_mov_b64 s[2:3], 0xc803000
	s_nop 0
	v_addc_co_u32_e32 v49, vcc, 0, v45, vcc
	global_load_dwordx2 v[92:93], v[46:47], off offset:512
	global_load_dwordx2 v[90:91], v[46:47], off offset:1024
	global_load_dwordx2 v[88:89], v[46:47], off offset:1536
	global_load_dwordx2 v[86:87], v[46:47], off offset:2048
	global_load_dwordx2 v[94:95], v[48:49], off
	global_load_dwordx2 v[84:85], v[46:47], off offset:2560
	global_load_dwordx2 v[82:83], v[46:47], off offset:3072
	global_load_dwordx2 v[80:81], v[46:47], off offset:3584
	v_lshl_add_u64 v[46:47], v[44:45], 0, s[2:3]
	s_mov_b32 s2, 0xc803000
	v_add_co_u32_e32 v44, vcc, s2, v44
	v_mbcnt_lo_u32_b32 v35, -1, 0
	s_nop 0
	v_addc_co_u32_e32 v45, vcc, 0, v45, vcc
	global_load_dwordx2 v[78:79], v[46:47], off offset:512
	global_load_dwordx2 v[76:77], v[46:47], off offset:1024
	global_load_dwordx2 v[74:75], v[46:47], off offset:1536
	global_load_dwordx2 v[72:73], v[46:47], off offset:2048
	global_load_dwordx2 v[96:97], v[44:45], off
	global_load_dwordx2 v[70:71], v[46:47], off offset:2560
	global_load_dwordx2 v[68:69], v[46:47], off offset:3072
	global_load_dwordx2 v[66:67], v[46:47], off offset:3584
	v_mbcnt_hi_u32_b32 v35, -1, v35
	v_and_b32_e32 v37, 64, v35
	v_add_u32_e32 v37, 64, v37
	v_xor_b32_e32 v39, 1, v35
	v_cmp_lt_i32_e32 vcc, v39, v37
	s_add_i32 s2, s0, s94
	s_ashr_i32 s3, s2, 31
	v_cndmask_b32_e32 v39, v35, v39, vcc
	v_lshlrev_b32_e32 v98, 2, v39
	v_xor_b32_e32 v39, 2, v35
	v_cmp_lt_i32_e32 vcc, v39, v37
	s_ashr_i32 s95, s94, 31
	s_lshl_b64 s[2:3], s[2:3], 12
	v_cndmask_b32_e32 v39, v35, v39, vcc
	v_lshlrev_b32_e32 v99, 2, v39
	v_xor_b32_e32 v39, 4, v35
	v_cmp_lt_i32_e32 vcc, v39, v37
	s_add_u32 s2, s6, s2
	s_addc_u32 s3, s7, s3
	v_cndmask_b32_e32 v39, v35, v39, vcc
	v_lshlrev_b32_e32 v100, 2, v39
	v_xor_b32_e32 v39, 8, v35
	v_cmp_lt_i32_e32 vcc, v39, v37
	v_lshl_add_u64 v[32:33], s[2:3], 0, v[32:33]
	s_mov_b64 s[2:3], 0xc803e00
	v_cndmask_b32_e32 v39, v35, v39, vcc
	v_lshlrev_b32_e32 v101, 2, v39
	v_xor_b32_e32 v39, 16, v35
	v_cmp_lt_i32_e32 vcc, v39, v37
	v_lshl_add_u64 v[32:33], v[32:33], 0, s[2:3]
	s_lshl_b64 s[2:3], s[94:95], 12
	v_cndmask_b32_e32 v39, v35, v39, vcc
	v_lshlrev_b32_e32 v102, 2, v39
	v_xor_b32_e32 v39, 32, v35
	v_cmp_lt_i32_e32 vcc, v39, v37
	s_mov_b64 s[6:7], 0
	v_mov_b32_e32 v104, 0x358637bd
	v_cndmask_b32_e32 v35, v35, v39, vcc
	v_lshlrev_b32_e32 v103, 2, v35
	s_mov_b32 s10, 0x800000
	v_lshlrev_b32_e32 v105, 4, v34
	v_lshlrev_b32_e32 v106, 4, v36
	v_lshlrev_b32_e32 v107, 4, v38
	v_lshlrev_b32_e32 v108, 4, v40
	v_lshlrev_b32_e32 v109, 4, v42
	s_mov_b32 s11, s0
	s_branch .LBB0_4914
.LBB0_4913:
	s_waitcnt vmcnt(15)
	v_lshlrev_b32_e32 v115, 16, v92
	v_and_b32_e32 v117, 0xffff0000, v92
	s_waitcnt vmcnt(11)
	v_and_b32_e32 v116, 0xffff0000, v94
	v_lshlrev_b32_e32 v119, 16, v93
	v_and_b32_e32 v93, 0xffff0000, v93
	v_and_b32_e32 v92, 0xffff0000, v95
	v_lshlrev_b32_e32 v114, 16, v94
	v_lshlrev_b32_e32 v118, 16, v95
	v_pk_mul_f32 v[94:95], v[116:117], v[116:117]
	v_pk_mul_f32 v[120:121], v[92:93], v[92:93]
	v_pk_fma_f32 v[94:95], v[114:115], v[114:115], v[94:95]
	v_pk_fma_f32 v[120:121], v[118:119], v[118:119], v[120:121]
	v_lshlrev_b32_e32 v124, 16, v88
	v_pk_add_f32 v[94:95], v[94:95], v[120:121]
	v_lshlrev_b32_e32 v121, 16, v91
	v_lshlrev_b32_e32 v120, 16, v90
	v_and_b32_e32 v91, 0xffff0000, v91
	v_and_b32_e32 v90, 0xffff0000, v90
	v_pk_add_f32 v[94:95], v[94:95], v[94:95] op_sel_hi:[0,1]
	v_pk_mul_f32 v[122:123], v[90:91], v[90:91]
	v_and_b32_e32 v125, 0xffff0000, v88
	v_lshlrev_b32_e32 v88, 16, v89
	v_lshlrev_b32_e32 v126, 16, v86
	v_pk_fma_f32 v[122:123], v[120:121], v[120:121], v[122:123]
	v_mul_f32_e32 v127, v124, v124
	v_mul_f32_e32 v129, v125, v125
	v_and_b32_e32 v89, 0xffff0000, v89
	v_mul_f32_e32 v94, v88, v88
	v_mov_b32_e32 v128, v126
	v_pk_add_f32 v[122:123], v[122:123], v[122:123] op_sel_hi:[0,1]
	v_pk_fma_f32 v[130:131], v[88:89], v[88:89], v[94:95] op_sel_hi:[1,1,0]
	v_and_b32_e32 v153, 0xffff0000, v86
	v_lshlrev_b32_e32 v86, 16, v87
	v_and_b32_e32 v87, 0xffff0000, v87
	v_pk_add_f32 v[128:129], v[126:127], v[128:129]
	v_mul_f32_e32 v130, v153, v153
	v_mul_f32_e32 v122, v86, v86
	v_mul_f32_e32 v94, v87, v87
	v_mul_f32_e32 v132, v126, v126
	v_mov_b32_e32 v133, v129
	v_pk_add_f32 v[128:129], v[132:133], v[130:131]
	v_pk_add_f32 v[94:95], v[122:123], v[94:95]
	s_waitcnt vmcnt(10)
	v_lshlrev_b32_e32 v123, 16, v85
	v_pk_add_f32 v[94:95], v[128:129], v[94:95]
	v_and_b32_e32 v129, 0xffff0000, v85
	v_and_b32_e32 v128, 0xffff0000, v84
	v_lshlrev_b32_e32 v122, 16, v84
	v_pk_mul_f32 v[84:85], v[128:129], v[128:129]
	s_waitcnt vmcnt(9)
	v_lshlrev_b32_e32 v130, 16, v82
	v_and_b32_e32 v131, 0xffff0000, v82
	v_lshlrev_b32_e32 v136, 16, v83
	s_waitcnt vmcnt(8)
	v_lshlrev_b32_e32 v132, 16, v80
	v_pk_fma_f32 v[84:85], v[122:123], v[122:123], v[84:85]
	v_mul_f32_e32 v133, v130, v130
	v_mul_f32_e32 v135, v131, v131
	v_and_b32_e32 v137, 0xffff0000, v83
	v_mul_f32_e32 v82, v136, v136
	v_mov_b32_e32 v134, v132
	v_pk_add_f32 v[94:95], v[94:95], v[94:95] op_sel_hi:[0,1]
	v_pk_add_f32 v[84:85], v[84:85], v[84:85] op_sel_hi:[0,1]
	v_pk_fma_f32 v[82:83], v[136:137], v[136:137], v[82:83] op_sel_hi:[1,1,0]
	v_and_b32_e32 v154, 0xffff0000, v80
	v_lshlrev_b32_e32 v138, 16, v81
	v_and_b32_e32 v139, 0xffff0000, v81
	v_pk_add_f32 v[134:135], v[132:133], v[134:135]
	v_mul_f32_e32 v82, v154, v154
	v_mul_f32_e32 v84, v138, v138
	v_mul_f32_e32 v94, v139, v139
	v_mul_f32_e32 v80, v132, v132
	v_mov_b32_e32 v81, v135
	v_pk_add_f32 v[80:81], v[80:81], v[82:83]
	v_pk_add_f32 v[82:83], v[84:85], v[94:95]
	s_waitcnt vmcnt(5)
	v_and_b32_e32 v85, 0xffff0000, v75
	v_mul_f32_e32 v85, v180, v85
	v_pk_add_f32 v[80:81], v[80:81], v[82:83]
	s_waitcnt vmcnt(4)
	v_lshlrev_b32_e32 v94, 16, v72
	v_mul_f32_e32 v94, v180, v94
	v_add_f32_e32 v81, v80, v81
	ds_bpermute_b32 v82, v98, v81
	v_lshlrev_b32_e32 v134, 16, v73
	v_mul_f32_e32 v134, v180, v134
	v_and_b32_e32 v135, 0xffff0000, v73
	v_mul_f32_e32 v135, v180, v135
	s_waitcnt vmcnt(2)
	v_lshlrev_b32_e32 v140, 16, v70
	v_mul_f32_e32 v140, v180, v140
	v_and_b32_e32 v141, 0xffff0000, v70
	v_mul_f32_e32 v141, v180, v141
	s_waitcnt lgkmcnt(0)
	v_add_f32_e32 v83, v81, v82
	ds_bpermute_b32 v84, v99, v83
	v_lshlrev_b32_e32 v82, 16, v74
	v_mul_f32_e32 v82, v180, v82
	v_lshlrev_b32_e32 v142, 16, v71
	v_mul_f32_e32 v142, v180, v142
	v_and_b32_e32 v143, 0xffff0000, v71
	v_mul_f32_e32 v143, v180, v143
	s_waitcnt vmcnt(1)
	v_lshlrev_b32_e32 v144, 16, v68
	v_mul_f32_e32 v144, v180, v144
	s_waitcnt lgkmcnt(0)
	v_add_f32_e32 v95, v83, v84
	ds_bpermute_b32 v127, v100, v95
	v_and_b32_e32 v83, 0xffff0000, v74
	v_mul_f32_e32 v83, v180, v83
	v_lshlrev_b32_e32 v84, 16, v75
	v_mul_f32_e32 v84, v180, v84
	v_and_b32_e32 v145, 0xffff0000, v68
	v_mul_f32_e32 v145, v180, v145
	v_lshlrev_b32_e32 v146, 16, v69
	v_mul_f32_e32 v146, v180, v146
	s_waitcnt lgkmcnt(0)
	v_add_f32_e32 v74, v95, v127
	ds_bpermute_b32 v75, v101, v74
	v_and_b32_e32 v95, 0xffff0000, v72
	v_mul_f32_e32 v95, v180, v95
	v_and_b32_e32 v147, 0xffff0000, v69
	v_mul_f32_e32 v147, v180, v147
	s_add_i32 s13, s11, 0xffffc000
	s_add_u32 s14, s0, s6
	s_waitcnt lgkmcnt(0)
	v_add_f32_e32 v72, v74, v75
	ds_bpermute_b32 v73, v102, v72
	s_waitcnt vmcnt(0)
	v_lshlrev_b32_e32 v148, 16, v66
	v_mul_f32_e32 v148, v180, v148
	v_and_b32_e32 v149, 0xffff0000, v66
	v_mul_f32_e32 v149, v180, v149
	s_addc_u32 s15, s1, s7
	s_cmpk_lt_i32 s11, 0x4000
	s_waitcnt lgkmcnt(0)
	v_add_f32_e32 v70, v72, v73
	ds_bpermute_b32 v71, v103, v70
	v_lshlrev_b32_e32 v112, 16, v78
	v_mul_f32_e32 v112, v180, v112
	v_and_b32_e32 v113, 0xffff0000, v78
	v_mul_f32_e32 v113, v180, v113
	v_lshlrev_b32_e32 v78, 16, v79
	v_mul_f32_e32 v78, v180, v78
	v_and_b32_e32 v79, 0xffff0000, v79
	v_mul_f32_e32 v79, v180, v79
	s_waitcnt lgkmcnt(0)
	v_add_f32_e32 v68, v70, v71
	v_fmamk_f32 v68, v68, 0x3a000000, v104
	v_mul_f32_e32 v69, 0x4b800000, v68
	v_cmp_gt_f32_e32 vcc, s10, v68
	v_mov_b32_e32 v74, v120
	v_mov_b32_e32 v75, v90
	v_cndmask_b32_e32 v68, v68, v69, vcc
	v_rsq_f32_e32 v68, v68
	v_mov_b32_e32 v69, v92
	v_mov_b32_e32 v92, v119
	v_mov_b32_e32 v90, v121
	v_mul_f32_e32 v66, 0x45800000, v68
	v_cndmask_b32_e32 v152, v68, v66, vcc
	v_pk_mul_f32 v[72:73], v[92:93], v[152:153] op_sel_hi:[1,0]
	s_cselect_b32 s11, 0, 0x8000000
	v_lshlrev_b32_e32 v80, 16, v76
	v_mul_f32_e32 v80, v180, v80
	v_and_b32_e32 v81, 0xffff0000, v76
	v_mul_f32_e32 v81, v180, v81
	v_lshlrev_b32_e32 v76, 16, v77
	v_mul_f32_e32 v76, v180, v76
	v_and_b32_e32 v77, 0xffff0000, v77
	v_mul_f32_e32 v77, v180, v77
	v_pk_fma_f32 v[72:73], v[6:7], v[72:73], v[78:79]
	v_pk_mul_f32 v[74:75], v[152:153], v[74:75] op_sel_hi:[0,1]
	v_pk_mul_f32 v[78:79], v[152:153], v[90:91] op_sel_hi:[0,1]
	s_cselect_b32 s15, s15, 0
	s_cselect_b32 s14, s14, s13
	s_add_u32 s11, s4, s11
	v_mov_b32_e32 v68, v118
	v_pk_fma_f32 v[76:77], v[10:11], v[78:79], v[76:77]
	v_pk_fma_f32 v[74:75], v[8:9], v[74:75], v[80:81]
	v_pk_mul_f32 v[78:79], v[124:125], v[152:153] op_sel_hi:[1,0]
	v_pk_mul_f32 v[80:81], v[88:89], v[152:153] op_sel_hi:[1,0]
	v_mov_b32_e32 v127, v153
	s_addc_u32 s13, s5, 0
	s_lshl_b64 s[14:15], s[14:15], 13
	v_lshlrev_b32_e32 v110, 16, v96
	v_mul_f32_e32 v110, v180, v110
	v_and_b32_e32 v111, 0xffff0000, v96
	v_mul_f32_e32 v111, v180, v111
	v_lshlrev_b32_e32 v96, 16, v97
	v_mul_f32_e32 v96, v180, v96
	v_and_b32_e32 v97, 0xffff0000, v97
	v_mul_f32_e32 v97, v180, v97
	v_lshlrev_b32_e32 v150, 16, v67
	v_mul_f32_e32 v150, v180, v150
	v_and_b32_e32 v151, 0xffff0000, v67
	v_mul_f32_e32 v151, v180, v151
	v_mov_b32_e32 v66, v114
	v_mov_b32_e32 v67, v116
	v_pk_mul_f32 v[68:69], v[68:69], v[152:153] op_sel_hi:[1,0]
	v_mov_b32_e32 v116, v115
	v_pk_fma_f32 v[80:81], v[14:15], v[80:81], v[84:85]
	v_pk_fma_f32 v[78:79], v[12:13], v[78:79], v[82:83]
	v_pk_mul_f32 v[82:83], v[126:127], v[152:153] op_sel_hi:[1,0]
	v_pk_mul_f32 v[84:85], v[86:87], v[152:153] op_sel_hi:[1,0]
	v_mov_b32_e32 v86, v122
	v_mov_b32_e32 v87, v128
	v_mov_b32_e32 v128, v123
	v_mov_b32_e32 v133, v154
	s_add_u32 s14, s11, s14
	v_pk_mul_f32 v[66:67], v[66:67], v[152:153] op_sel_hi:[1,0]
	v_pk_fma_f32 v[68:69], v[2:3], v[68:69], v[96:97]
	v_pk_mul_f32 v[70:71], v[116:117], v[152:153] op_sel_hi:[1,0]
	v_pk_fma_f32 v[82:83], v[16:17], v[82:83], v[94:95]
	v_pk_mul_f32 v[86:87], v[152:153], v[86:87] op_sel_hi:[0,1]
	v_pk_mul_f32 v[88:89], v[152:153], v[128:129] op_sel_hi:[0,1]
	v_pk_mul_f32 v[90:91], v[130:131], v[152:153] op_sel_hi:[1,0]
	v_pk_mul_f32 v[92:93], v[136:137], v[152:153] op_sel_hi:[1,0]
	v_pk_mul_f32 v[94:95], v[132:133], v[152:153] op_sel_hi:[1,0]
	v_pk_mul_f32 v[96:97], v[138:139], v[152:153] op_sel_hi:[1,0]
	s_addc_u32 s15, s13, s15
	v_pk_fma_f32 v[66:67], v[0:1], v[66:67], v[110:111]
	v_pk_fma_f32 v[70:71], v[4:5], v[70:71], v[112:113]
	v_pk_fma_f32 v[84:85], v[18:19], v[84:85], v[134:135]
	v_pk_fma_f32 v[88:89], v[22:23], v[88:89], v[142:143]
	v_pk_fma_f32 v[86:87], v[20:21], v[86:87], v[140:141]
	v_pk_fma_f32 v[92:93], v[26:27], v[92:93], v[146:147]
	v_pk_fma_f32 v[90:91], v[24:25], v[90:91], v[144:145]
	v_pk_fma_f32 v[96:97], v[30:31], v[96:97], v[150:151]
	v_pk_fma_f32 v[94:95], v[28:29], v[94:95], v[148:149]
	s_add_u32 s6, s6, s94
	global_store_dwordx4 v105, v[66:69], s[14:15]
	global_store_dwordx4 v105, v[70:73], s[14:15] offset:1024
	global_store_dwordx4 v105, v[74:77], s[14:15] offset:2048
	global_store_dwordx4 v105, v[78:81], s[14:15] offset:3072
	global_store_dwordx4 v106, v[82:85], s[14:15]
	global_store_dwordx4 v107, v[86:89], s[14:15]
	global_store_dwordx4 v108, v[90:93], s[14:15]
	global_store_dwordx4 v109, v[94:97], s[14:15]
	s_addc_u32 s7, s7, s95
	v_lshl_add_u64 v[32:33], v[32:33], 0, s[2:3]
	s_andn2_b64 vcc, exec, s[8:9]
	s_mov_b32 s11, s12
	v_mov_b32_e32 v94, v34
	v_mov_b32_e32 v95, v35
	v_mov_b32_e32 v92, v36
	v_mov_b32_e32 v93, v37
	v_mov_b32_e32 v90, v38
	v_mov_b32_e32 v91, v39
	v_mov_b32_e32 v88, v40
	v_mov_b32_e32 v89, v41
	v_mov_b32_e32 v86, v58
	v_mov_b32_e32 v87, v59
	v_mov_b32_e32 v84, v60
	v_mov_b32_e32 v85, v61
	v_mov_b32_e32 v82, v62
	v_mov_b32_e32 v83, v63
	v_mov_b32_e32 v80, v64
	v_mov_b32_e32 v81, v65
	v_mov_b32_e32 v96, v54
	v_mov_b32_e32 v97, v55
	v_mov_b32_e32 v78, v52
	v_mov_b32_e32 v79, v53
	v_mov_b32_e32 v76, v50
	v_mov_b32_e32 v77, v51
	v_mov_b32_e32 v74, v48
	v_mov_b32_e32 v75, v49
	v_mov_b32_e32 v72, v46
	v_mov_b32_e32 v73, v47
	v_mov_b32_e32 v70, v44
	v_mov_b32_e32 v71, v45
	v_mov_b32_e32 v68, v42
	v_mov_b32_e32 v69, v43
	v_mov_b32_e32 v66, v56
	v_mov_b32_e32 v67, v57
	v_mov_b32_e32 v180, v181
	s_cbranch_vccz .LBB0_4916
.LBB0_4914:
	s_add_i32 s12, s11, s94
	s_cmpk_gt_i32 s12, 0x407f
	s_cselect_b64 s[8:9], -1, 0
	s_and_b64 vcc, exec, s[8:9]
	s_cbranch_vccnz .LBB0_4913
	v_add_co_u32_e32 v178, vcc, 0x23080000, v32
	s_nop 1
	v_addc_co_u32_e32 v179, vcc, 0, v33, vcc
	global_load_dword v181, v[178:179], off offset:-2560
	v_add_co_u32_e32 v56, vcc, 0x1ef80000, v32
	s_nop 1
	v_addc_co_u32_e32 v57, vcc, 0, v33, vcc
	global_load_dwordx2 v[34:35], v[56:57], off offset:-3584
	global_load_dwordx2 v[36:37], v[56:57], off offset:-3072
	global_load_dwordx2 v[38:39], v[56:57], off offset:-2560
	global_load_dwordx2 v[40:41], v[56:57], off offset:-2048
	global_load_dwordx2 v[58:59], v[56:57], off offset:-1536
	global_load_dwordx2 v[60:61], v[56:57], off offset:-1024
	global_load_dwordx2 v[62:63], v[56:57], off offset:-512
	global_load_dwordx2 v[64:65], v[56:57], off
	global_load_dwordx2 v[54:55], v[32:33], off offset:-3584
	global_load_dwordx2 v[52:53], v[32:33], off offset:-3072
	global_load_dwordx2 v[50:51], v[32:33], off offset:-2560
	global_load_dwordx2 v[48:49], v[32:33], off offset:-2048
	global_load_dwordx2 v[46:47], v[32:33], off offset:-1536
	global_load_dwordx2 v[44:45], v[32:33], off offset:-1024
	global_load_dwordx2 v[42:43], v[32:33], off offset:-512
	global_load_dwordx2 v[56:57], v[32:33], off
	s_branch .LBB0_4913
